# speedup vs baseline: 1.0026x; 1.0026x over previous
;   #define LDA(dst,b,h) for(int m=0;m<4;++m)for(int k=0;k<2;++k) \
;     dst[m][k]=*reinterpret_cast<const bf16x8*>((char*)SA(b,h)+lds_byte(wr*64+m*16+fr,k*32+fq*8))
;   #define LDB(dst,b,h) for(int n=0;n<2;++n)for(int k=0;k<2;++k) \
;     dst[n][k]=*reinterpret_cast<const bf16x8*>((char*)SB(b,h)+lds_byte(wc*32+n*16+fr,k*32+fq*8))
;   #define MMA(ai,bj,At,Bt_) do{__builtin_amdgcn_s_setprio(1); \
;     for(int m=0;m<4;++m)for(int n=0;n<2;++n)for(int k=0;k<2;++k) \
;       acc[ai][bj][m][n]=__builtin_amdgcn_mfma_f32_16x16x32_bf16(Bt_[n][k],At[m][k],acc[ai][bj][m][n],0,0,0); \
;     __builtin_amdgcn_s_setprio(0);}while(0)
;   #define WAIT_V(n) asm volatile("s_waitcnt vmcnt(" #n ")":::"memory")
;   #define WAIT_L(n) asm volatile("s_waitcnt lgkmcnt(" #n ")":::"memory")
;   #define BAR __builtin_amdgcn_s_barrier()
;   #define SCHED __builtin_amdgcn_sched_barrier(0)
; template <bool TWO, class MID> ...
;     ...
;   for(int t=0;t<nt-2;t+=2){
;     if (TWO && t == nt1) mid();
;     LDB(B0,0,0); SCHED; LDA(At,0,0); STAGE_A(SA(1,1),1,t+1);
;     WAIT_L(8); BAR; WAIT_L(0); MMA(0,0,At,B0); BAR; SCHED;
;     LDB(B1,0,1); STAGE_B(SB(0,0),0,t+2);
;     BAR; WAIT_L(0); MMA(0,1,At,B1); BAR;
;     LDA(At,0,1); STAGE_A(SA(0,0),0,t+2);
;     BAR; WAIT_L(0); MMA(1,0,At,B0); BAR; SCHED;
;     STAGE_B(SB(0,1),1,t+2);
;     WAIT_V(6); BAR; MMA(1,1,At,B1); BAR;
.LBB0_169:
	ds_read_b128 v[170:173], v143
	ds_read_b128 v[174:177], v143 offset:1024
	ds_read_b128 v[178:181], v143 offset:2048
	ds_read_b128 v[182:185], v143 offset:3072
	ds_read_b128 v[186:189], v168
	ds_read_b128 v[190:193], v168 offset:1024
	ds_read_b128 v[196:199], v167
	ds_read_b128 v[200:203], v167 offset:1024
	ds_read_b128 v[204:207], v166
	ds_read_b128 v[208:211], v166 offset:1024
	ds_read_b128 v[212:215], v147
	ds_read_b128 v[216:219], v147 offset:1024
	s_add_u32 s17, s0, s12
	s_addc_u32 s18, s1, s13
	s_add_u32 m0, s98, 0xc000
	s_add_u32 s20, s17, 0x8080080
	s_addc_u32 s21, s18, 0
	global_load_lds_dwordx4 v132, s[20:21]
	s_add_u32 m0, s98, 0xe000
	s_setprio 1
	global_load_lds_dwordx4 v130, s[20:21]
	s_waitcnt lgkmcnt(8)
	s_barrier
	s_waitcnt lgkmcnt(0)
	v_mfma_f32_16x16x32_bf16 v[126:129], v[170:173], v[186:189], v[126:129]
	v_mfma_f32_16x16x32_bf16 v[122:125], v[178:181], v[186:189], v[122:125]
	v_mfma_f32_16x16x32_bf16 v[118:121], v[170:173], v[196:199], v[118:121]
	v_mfma_f32_16x16x32_bf16 v[114:117], v[178:181], v[196:199], v[114:117]
	v_mfma_f32_16x16x32_bf16 v[110:113], v[170:173], v[204:207], v[110:113]
	v_mfma_f32_16x16x32_bf16 v[106:109], v[178:181], v[204:207], v[106:109]
	v_mfma_f32_16x16x32_bf16 v[102:105], v[170:173], v[212:215], v[102:105]
	v_mfma_f32_16x16x32_bf16 v[98:101], v[178:181], v[212:215], v[98:101]
	v_mfma_f32_16x16x32_bf16 v[126:129], v[174:177], v[190:193], v[126:129]
	v_mfma_f32_16x16x32_bf16 v[122:125], v[182:185], v[190:193], v[122:125]
	v_mfma_f32_16x16x32_bf16 v[118:121], v[174:177], v[200:203], v[118:121]
	v_mfma_f32_16x16x32_bf16 v[114:117], v[182:185], v[200:203], v[114:117]
	v_mfma_f32_16x16x32_bf16 v[110:113], v[174:177], v[208:211], v[110:113]
	v_mfma_f32_16x16x32_bf16 v[106:109], v[182:185], v[208:211], v[106:109]
	v_mfma_f32_16x16x32_bf16 v[102:105], v[174:177], v[216:219], v[102:105]
	v_mfma_f32_16x16x32_bf16 v[98:101], v[182:185], v[216:219], v[98:101]
	s_barrier
	s_setprio 0
	s_add_u32 s19, s0, s14
	ds_read_b128 v[220:223], v141
	ds_read_b128 v[224:227], v141 offset:1024
	ds_read_b128 v[228:231], v141 offset:2048
	ds_read_b128 v[232:235], v141 offset:3072
	s_addc_u32 s20, s1, s15
	s_add_u32 m0, s98, 0x10000
	s_add_u32 s26, s19, 0x100
	s_addc_u32 s27, s20, 0
	global_load_lds_dwordx4 v132, s[26:27]
	s_add_u32 m0, s98, 0x12000
	s_setprio 1
	global_load_lds_dwordx4 v130, s[26:27]
	s_barrier
	s_waitcnt lgkmcnt(0)
	v_mfma_f32_16x16x32_bf16 v[94:97], v[220:223], v[186:189], v[94:97]
	v_mfma_f32_16x16x32_bf16 v[90:93], v[228:231], v[186:189], v[90:93]
	v_mfma_f32_16x16x32_bf16 v[86:89], v[220:223], v[196:199], v[86:89]
	v_mfma_f32_16x16x32_bf16 v[82:85], v[228:231], v[196:199], v[82:85]
	v_mfma_f32_16x16x32_bf16 v[78:81], v[220:223], v[204:207], v[78:81]
	v_mfma_f32_16x16x32_bf16 v[74:77], v[228:231], v[204:207], v[74:77]
	v_mfma_f32_16x16x32_bf16 v[70:73], v[220:223], v[212:215], v[70:73]
	v_mfma_f32_16x16x32_bf16 v[66:69], v[228:231], v[212:215], v[66:69]
	v_mfma_f32_16x16x32_bf16 v[94:97], v[224:227], v[190:193], v[94:97]
	v_mfma_f32_16x16x32_bf16 v[90:93], v[232:235], v[190:193], v[90:93]
	v_mfma_f32_16x16x32_bf16 v[86:89], v[224:227], v[200:203], v[86:89]
	v_mfma_f32_16x16x32_bf16 v[82:85], v[232:235], v[200:203], v[82:85]
	v_mfma_f32_16x16x32_bf16 v[78:81], v[224:227], v[208:211], v[78:81]
	v_mfma_f32_16x16x32_bf16 v[74:77], v[232:235], v[208:211], v[74:77]
	v_mfma_f32_16x16x32_bf16 v[70:73], v[224:227], v[216:219], v[70:73]
	v_mfma_f32_16x16x32_bf16 v[66:69], v[232:235], v[216:219], v[66:69]
	s_barrier
	s_setprio 0
	ds_read_b128 v[186:189], v168 offset:16384
	ds_read_b128 v[190:193], v168 offset:17408
	ds_read_b128 v[196:199], v167 offset:16384
	ds_read_b128 v[200:203], v167 offset:17408
	ds_read_b128 v[204:207], v166 offset:16384
	ds_read_b128 v[208:211], v166 offset:17408
	ds_read_b128 v[212:215], v147 offset:16384
	ds_read_b128 v[216:219], v147 offset:17408
	s_add_u32 m0, s98, 0x0
	s_add_u32 s26, s17, 0x8000100
	s_addc_u32 s27, s18, 0
	global_load_lds_dwordx4 v132, s[26:27]
	s_add_u32 m0, s98, 0x2000
	s_setprio 1
	global_load_lds_dwordx4 v130, s[26:27]
	s_barrier
	s_waitcnt lgkmcnt(0)
	v_mfma_f32_16x16x32_bf16 v[62:65], v[170:173], v[186:189], v[62:65]
	v_mfma_f32_16x16x32_bf16 v[58:61], v[178:181], v[186:189], v[58:61]
	v_mfma_f32_16x16x32_bf16 v[54:57], v[170:173], v[196:199], v[54:57]
	v_mfma_f32_16x16x32_bf16 v[50:53], v[178:181], v[196:199], v[50:53]
	v_mfma_f32_16x16x32_bf16 v[46:49], v[170:173], v[204:207], v[46:49]
	v_mfma_f32_16x16x32_bf16 v[42:45], v[178:181], v[204:207], v[42:45]
	v_mfma_f32_16x16x32_bf16 v[38:41], v[170:173], v[212:215], v[38:41]
	v_mfma_f32_16x16x32_bf16 v[34:37], v[178:181], v[212:215], v[34:37]
	v_mfma_f32_16x16x32_bf16 v[62:65], v[174:177], v[190:193], v[62:65]
	v_mfma_f32_16x16x32_bf16 v[58:61], v[182:185], v[190:193], v[58:61]
	v_mfma_f32_16x16x32_bf16 v[54:57], v[174:177], v[200:203], v[54:57]
	v_mfma_f32_16x16x32_bf16 v[50:53], v[182:185], v[200:203], v[50:53]
	v_mfma_f32_16x16x32_bf16 v[46:49], v[174:177], v[208:211], v[46:49]
	v_mfma_f32_16x16x32_bf16 v[42:45], v[182:185], v[208:211], v[42:45]
	v_mfma_f32_16x16x32_bf16 v[38:41], v[174:177], v[216:219], v[38:41]
	v_mfma_f32_16x16x32_bf16 v[34:37], v[182:185], v[216:219], v[34:37]
	s_barrier
	s_setprio 0
	s_add_u32 m0, s98, 0x14000
	s_add_u32 s26, s19, 0x80100
	s_addc_u32 s27, s20, 0
	global_load_lds_dwordx4 v132, s[26:27]
	s_add_u32 m0, s98, 0x16000
	s_setprio 1
	global_load_lds_dwordx4 v130, s[26:27]
	s_waitcnt vmcnt(6)
	s_barrier
;   #define LDA(dst,b,h) for(int m=0;m<4;++m)for(int k=0;k<2;++k) \
;     dst[m][k]=*reinterpret_cast<const bf16x8*>((char*)SA(b,h)+lds_byte(wr*64+m*16+fr,k*32+fq*8))
;   #define LDB(dst,b,h) for(int n=0;n<2;++n)for(int k=0;k<2;++k) \
;     dst[n][k]=*reinterpret_cast<const bf16x8*>((char*)SB(b,h)+lds_byte(wc*32+n*16+fr,k*32+fq*8))
;   #define MMA(ai,bj,At,Bt_) do{__builtin_amdgcn_s_setprio(1); \
;     for(int m=0;m<4;++m)for(int n=0;n<2;++n)for(int k=0;k<2;++k) \
;       acc[ai][bj][m][n]=__builtin_amdgcn_mfma_f32_16x16x32_bf16(Bt_[n][k],At[m][k],acc[ai][bj][m][n],0,0,0); \
;     __builtin_amdgcn_s_setprio(0);}while(0)
;   #define WAIT_V(n) asm volatile("s_waitcnt vmcnt(" #n ")":::"memory")
;   #define WAIT_L(n) asm volatile("s_waitcnt lgkmcnt(" #n ")":::"memory")
;   #define BAR __builtin_amdgcn_s_barrier()
;   #define SCHED __builtin_amdgcn_sched_barrier(0)
; template <bool TWO, class MID> ...
;     ...
;     WAIT_V(6); BAR; MMA(1,1,At,B1); BAR;
;     LDB(B0,1,0); SCHED; LDA(At,1,0); STAGE_A(SA(0,1),1,t+2);
;     WAIT_L(8); BAR; WAIT_L(0); MMA(0,0,At,B0); BAR; SCHED;
;     LDB(B1,1,1); STAGE_B(SB(1,0),0,t+3);
;     BAR; WAIT_L(0); MMA(0,1,At,B1); BAR;
;     LDA(At,1,1); STAGE_A(SA(1,0),0,t+3);
;     BAR; WAIT_L(0); MMA(1,0,At,B0); BAR; SCHED;
	v_mfma_f32_16x16x32_bf16 v[30:33], v[220:223], v[186:189], v[30:33]
	v_mfma_f32_16x16x32_bf16 v[26:29], v[228:231], v[186:189], v[26:29]
	v_mfma_f32_16x16x32_bf16 v[22:25], v[220:223], v[196:199], v[22:25]
	v_mfma_f32_16x16x32_bf16 v[18:21], v[228:231], v[196:199], v[18:21]
	v_mfma_f32_16x16x32_bf16 v[14:17], v[220:223], v[204:207], v[14:17]
	v_mfma_f32_16x16x32_bf16 v[10:13], v[228:231], v[204:207], v[10:13]
	v_mfma_f32_16x16x32_bf16 v[6:9], v[220:223], v[212:215], v[6:9]
	v_mfma_f32_16x16x32_bf16 v[2:5], v[228:231], v[212:215], v[2:5]
	v_mfma_f32_16x16x32_bf16 v[30:33], v[224:227], v[190:193], v[30:33]
	v_mfma_f32_16x16x32_bf16 v[26:29], v[232:235], v[190:193], v[26:29]
	v_mfma_f32_16x16x32_bf16 v[22:25], v[224:227], v[200:203], v[22:25]
	v_mfma_f32_16x16x32_bf16 v[18:21], v[232:235], v[200:203], v[18:21]
	v_mfma_f32_16x16x32_bf16 v[14:17], v[224:227], v[208:211], v[14:17]
	v_mfma_f32_16x16x32_bf16 v[10:13], v[232:235], v[208:211], v[10:13]
	v_mfma_f32_16x16x32_bf16 v[6:9], v[224:227], v[216:219], v[6:9]
	v_mfma_f32_16x16x32_bf16 v[2:5], v[232:235], v[216:219], v[2:5]
	s_barrier
	s_setprio 0
	ds_read_b128 v[170:173], v137
	ds_read_b128 v[174:177], v137 offset:1024
	ds_read_b128 v[178:181], v137 offset:2048
	ds_read_b128 v[182:185], v137 offset:3072
	ds_read_b128 v[186:189], v168 offset:32768
	ds_read_b128 v[190:193], v168 offset:33792
	ds_read_b128 v[196:199], v167 offset:32768
	ds_read_b128 v[200:203], v167 offset:33792
	ds_read_b128 v[204:207], v166 offset:32768
	ds_read_b128 v[208:211], v166 offset:33792
	ds_read_b128 v[212:215], v147 offset:32768
	ds_read_b128 v[216:219], v147 offset:33792
	s_add_u32 m0, s98, 0x4000
	s_add_u32 s26, s17, 0x8080100
	s_addc_u32 s27, s18, 0
	global_load_lds_dwordx4 v132, s[26:27]
	s_add_u32 m0, s98, 0x6000
	s_setprio 1
	global_load_lds_dwordx4 v130, s[26:27]
	s_waitcnt lgkmcnt(8)
	s_barrier
	s_waitcnt lgkmcnt(0)
	v_mfma_f32_16x16x32_bf16 v[126:129], v[170:173], v[186:189], v[126:129]
	v_mfma_f32_16x16x32_bf16 v[122:125], v[178:181], v[186:189], v[122:125]
	v_mfma_f32_16x16x32_bf16 v[118:121], v[170:173], v[196:199], v[118:121]
	v_mfma_f32_16x16x32_bf16 v[114:117], v[178:181], v[196:199], v[114:117]
	v_mfma_f32_16x16x32_bf16 v[110:113], v[170:173], v[204:207], v[110:113]
	v_mfma_f32_16x16x32_bf16 v[106:109], v[178:181], v[204:207], v[106:109]
	v_mfma_f32_16x16x32_bf16 v[102:105], v[170:173], v[212:215], v[102:105]
	v_mfma_f32_16x16x32_bf16 v[98:101], v[178:181], v[212:215], v[98:101]
	v_mfma_f32_16x16x32_bf16 v[126:129], v[174:177], v[190:193], v[126:129]
	v_mfma_f32_16x16x32_bf16 v[122:125], v[182:185], v[190:193], v[122:125]
	v_mfma_f32_16x16x32_bf16 v[118:121], v[174:177], v[200:203], v[118:121]
	v_mfma_f32_16x16x32_bf16 v[114:117], v[182:185], v[200:203], v[114:117]
	v_mfma_f32_16x16x32_bf16 v[110:113], v[174:177], v[208:211], v[110:113]
	v_mfma_f32_16x16x32_bf16 v[106:109], v[182:185], v[208:211], v[106:109]
	v_mfma_f32_16x16x32_bf16 v[102:105], v[174:177], v[216:219], v[102:105]
	v_mfma_f32_16x16x32_bf16 v[98:101], v[182:185], v[216:219], v[98:101]
	s_barrier
	s_setprio 0
	ds_read_b128 v[220:223], v135
	ds_read_b128 v[224:227], v135 offset:1024
	ds_read_b128 v[228:231], v135 offset:2048
	ds_read_b128 v[232:235], v135 offset:3072
	s_add_u32 m0, s98, 0x18000
	s_add_u32 s26, s19, 0x180
	s_addc_u32 s27, s20, 0
	global_load_lds_dwordx4 v132, s[26:27]
	s_add_u32 m0, s98, 0x1a000
	s_setprio 1
	global_load_lds_dwordx4 v130, s[26:27]
	s_barrier
	s_waitcnt lgkmcnt(0)
	v_mfma_f32_16x16x32_bf16 v[94:97], v[220:223], v[186:189], v[94:97]
	v_mfma_f32_16x16x32_bf16 v[90:93], v[228:231], v[186:189], v[90:93]
	v_mfma_f32_16x16x32_bf16 v[86:89], v[220:223], v[196:199], v[86:89]
	v_mfma_f32_16x16x32_bf16 v[82:85], v[228:231], v[196:199], v[82:85]
	v_mfma_f32_16x16x32_bf16 v[78:81], v[220:223], v[204:207], v[78:81]
	v_mfma_f32_16x16x32_bf16 v[74:77], v[228:231], v[204:207], v[74:77]
	v_mfma_f32_16x16x32_bf16 v[70:73], v[220:223], v[212:215], v[70:73]
	v_mfma_f32_16x16x32_bf16 v[66:69], v[228:231], v[212:215], v[66:69]
	v_mfma_f32_16x16x32_bf16 v[94:97], v[224:227], v[190:193], v[94:97]
	v_mfma_f32_16x16x32_bf16 v[90:93], v[232:235], v[190:193], v[90:93]
	v_mfma_f32_16x16x32_bf16 v[86:89], v[224:227], v[200:203], v[86:89]
	v_mfma_f32_16x16x32_bf16 v[82:85], v[232:235], v[200:203], v[82:85]
	v_mfma_f32_16x16x32_bf16 v[78:81], v[224:227], v[208:211], v[78:81]
	v_mfma_f32_16x16x32_bf16 v[74:77], v[232:235], v[208:211], v[74:77]
	v_mfma_f32_16x16x32_bf16 v[70:73], v[224:227], v[216:219], v[70:73]
	v_mfma_f32_16x16x32_bf16 v[66:69], v[232:235], v[216:219], v[66:69]
	s_barrier
	s_setprio 0
	ds_read_b128 v[186:189], v168 offset:49152
	ds_read_b128 v[190:193], v168 offset:50176
	ds_read_b128 v[196:199], v167 offset:49152
	ds_read_b128 v[200:203], v167 offset:50176
	ds_read_b128 v[204:207], v166 offset:49152
	ds_read_b128 v[208:211], v166 offset:50176
	ds_read_b128 v[212:215], v147 offset:49152
	ds_read_b128 v[216:219], v147 offset:50176
	s_add_u32 m0, s98, 0x8000
	s_add_u32 s26, s17, 0x8000180
	s_addc_u32 s27, s18, 0
	global_load_lds_dwordx4 v132, s[26:27]
	s_add_u32 m0, s98, 0xa000
	s_setprio 1
	global_load_lds_dwordx4 v130, s[26:27]
	s_barrier
;   #define LDA(dst,b,h) for(int m=0;m<4;++m)for(int k=0;k<2;++k) \
;     dst[m][k]=*reinterpret_cast<const bf16x8*>((char*)SA(b,h)+lds_byte(wr*64+m*16+fr,k*32+fq*8))
;   #define LDB(dst,b,h) for(int n=0;n<2;++n)for(int k=0;k<2;++k) \
;     dst[n][k]=*reinterpret_cast<const bf16x8*>((char*)SB(b,h)+lds_byte(wc*32+n*16+fr,k*32+fq*8))
;   #define MMA(ai,bj,At,Bt_) do{__builtin_amdgcn_s_setprio(1); \
;     for(int m=0;m<4;++m)for(int n=0;n<2;++n)for(int k=0;k<2;++k) \
;       acc[ai][bj][m][n]=__builtin_amdgcn_mfma_f32_16x16x32_bf16(Bt_[n][k],At[m][k],acc[ai][bj][m][n],0,0,0); \
;     __builtin_amdgcn_s_setprio(0);}while(0)
;   #define WAIT_V(n) asm volatile("s_waitcnt vmcnt(" #n ")":::"memory")
;   #define WAIT_L(n) asm volatile("s_waitcnt lgkmcnt(" #n ")":::"memory")
;   #define BAR __builtin_amdgcn_s_barrier()
;   #define SCHED __builtin_amdgcn_sched_barrier(0)
; template <bool TWO, class MID> ...
;     ...
;     BAR; WAIT_L(0); MMA(1,0,At,B0); BAR; SCHED;
;     STAGE_B(SB(1,1),1,t+3);
;     WAIT_V(6); BAR; MMA(1,1,At,B1); BAR;
;   }
;   { LDB(B0,0,0); LDA(At,0,0); STAGE_A(SA(1,1),1,nt-1);
;     BAR; WAIT_L(0); MMA(0,0,At,B0); BAR;
;     LDB(B1,0,1); BAR; WAIT_L(0); MMA(0,1,At,B1); BAR;
;     LDA(At,0,1); WAIT_V(4); BAR; WAIT_L(0); MMA(1,0,At,B0); MMA(1,1,At,B1); BAR; }
	s_waitcnt lgkmcnt(0)
	v_mfma_f32_16x16x32_bf16 v[62:65], v[170:173], v[186:189], v[62:65]
	v_mfma_f32_16x16x32_bf16 v[58:61], v[178:181], v[186:189], v[58:61]
	v_mfma_f32_16x16x32_bf16 v[54:57], v[170:173], v[196:199], v[54:57]
	v_mfma_f32_16x16x32_bf16 v[50:53], v[178:181], v[196:199], v[50:53]
	v_mfma_f32_16x16x32_bf16 v[46:49], v[170:173], v[204:207], v[46:49]
	v_mfma_f32_16x16x32_bf16 v[42:45], v[178:181], v[204:207], v[42:45]
	v_mfma_f32_16x16x32_bf16 v[38:41], v[170:173], v[212:215], v[38:41]
	v_mfma_f32_16x16x32_bf16 v[34:37], v[178:181], v[212:215], v[34:37]
	v_mfma_f32_16x16x32_bf16 v[62:65], v[174:177], v[190:193], v[62:65]
	v_mfma_f32_16x16x32_bf16 v[58:61], v[182:185], v[190:193], v[58:61]
	v_mfma_f32_16x16x32_bf16 v[54:57], v[174:177], v[200:203], v[54:57]
	v_mfma_f32_16x16x32_bf16 v[50:53], v[182:185], v[200:203], v[50:53]
	v_mfma_f32_16x16x32_bf16 v[46:49], v[174:177], v[208:211], v[46:49]
	v_mfma_f32_16x16x32_bf16 v[42:45], v[182:185], v[208:211], v[42:45]
	v_mfma_f32_16x16x32_bf16 v[38:41], v[174:177], v[216:219], v[38:41]
	v_mfma_f32_16x16x32_bf16 v[34:37], v[182:185], v[216:219], v[34:37]
	s_barrier
	s_setprio 0
	s_add_u32 m0, s98, 0x1c000
	s_add_u32 s18, s19, 0x80180
	s_addc_u32 s19, s20, 0
	global_load_lds_dwordx4 v132, s[18:19]
	s_add_u32 m0, s98, 0x1e000
	s_setprio 1
	global_load_lds_dwordx4 v130, s[18:19]
	s_waitcnt vmcnt(6)
	s_barrier
	v_mfma_f32_16x16x32_bf16 v[30:33], v[220:223], v[186:189], v[30:33]
	v_mfma_f32_16x16x32_bf16 v[26:29], v[228:231], v[186:189], v[26:29]
	v_mfma_f32_16x16x32_bf16 v[22:25], v[220:223], v[196:199], v[22:25]
	v_mfma_f32_16x16x32_bf16 v[18:21], v[228:231], v[196:199], v[18:21]
	v_mfma_f32_16x16x32_bf16 v[14:17], v[220:223], v[204:207], v[14:17]
	v_mfma_f32_16x16x32_bf16 v[10:13], v[228:231], v[204:207], v[10:13]
	v_mfma_f32_16x16x32_bf16 v[6:9], v[220:223], v[212:215], v[6:9]
	v_mfma_f32_16x16x32_bf16 v[2:5], v[228:231], v[212:215], v[2:5]
	v_mfma_f32_16x16x32_bf16 v[30:33], v[224:227], v[190:193], v[30:33]
	v_mfma_f32_16x16x32_bf16 v[26:29], v[232:235], v[190:193], v[26:29]
	v_mfma_f32_16x16x32_bf16 v[22:25], v[224:227], v[200:203], v[22:25]
	v_mfma_f32_16x16x32_bf16 v[18:21], v[232:235], v[200:203], v[18:21]
	v_mfma_f32_16x16x32_bf16 v[14:17], v[224:227], v[208:211], v[14:17]
	v_mfma_f32_16x16x32_bf16 v[10:13], v[232:235], v[208:211], v[10:13]
	v_mfma_f32_16x16x32_bf16 v[6:9], v[224:227], v[216:219], v[6:9]
	v_mfma_f32_16x16x32_bf16 v[2:5], v[232:235], v[216:219], v[2:5]
	s_setprio 0
	s_add_i32 s9, s9, 2
	s_add_u32 s0, s0, 0x100
	s_addc_u32 s1, s1, 0
	s_cmp_lt_u32 s9, 28
	s_barrier
	s_cbranch_scc1 .LBB0_169
	ds_read_b128 v[150:153], v143
	ds_read_b128 v[158:161], v143 offset:1024
	ds_read_b128 v[162:165], v143 offset:2048
	ds_read_b128 v[142:145], v143 offset:3072
	ds_read_b128 v[170:173], v168
	ds_read_b128 v[174:177], v168 offset:1024
	ds_read_b128 v[178:181], v167
	ds_read_b128 v[182:185], v167 offset:1024
	ds_read_b128 v[186:189], v166
	ds_read_b128 v[190:193], v166 offset:1024
	ds_read_b128 v[196:199], v147
	ds_read_b128 v[200:203], v147 offset:1024
	s_add_u32 s0, s11, 0x80f80
	s_addc_u32 s1, s16, 0
	v_lshl_add_u64 v[132:133], s[0:1], 0, v[132:133]
	v_readfirstlane_b32 s9, v148
	s_mov_b32 m0, s9
	global_load_lds_dwordx4 v[132:133], off
	v_lshl_add_u64 v[130:131], s[0:1], 0, v[130:131]
	v_readfirstlane_b32 s0, v156
	s_mov_b32 m0, s0
	global_load_lds_dwordx4 v[130:131], off
	s_setprio 1
	s_barrier
	s_waitcnt lgkmcnt(0)
	v_mfma_f32_16x16x32_bf16 v[126:129], v[150:153], v[170:173], v[126:129]
	v_mfma_f32_16x16x32_bf16 v[122:125], v[162:165], v[170:173], v[122:125]
	v_mfma_f32_16x16x32_bf16 v[114:117], v[162:165], v[178:181], v[114:117]
	v_mfma_f32_16x16x32_bf16 v[106:109], v[162:165], v[186:189], v[106:109]
	v_mfma_f32_16x16x32_bf16 v[98:101], v[162:165], v[196:199], v[98:101]
	v_mfma_f32_16x16x32_bf16 v[126:129], v[158:161], v[174:177], v[126:129]
	v_mfma_f32_16x16x32_bf16 v[122:125], v[142:145], v[174:177], v[122:125]
	v_mfma_f32_16x16x32_bf16 v[118:121], v[150:153], v[178:181], v[118:121]
	v_mfma_f32_16x16x32_bf16 v[114:117], v[142:145], v[182:185], v[114:117]
	v_mfma_f32_16x16x32_bf16 v[110:113], v[150:153], v[186:189], v[110:113]
	v_mfma_f32_16x16x32_bf16 v[106:109], v[142:145], v[190:193], v[106:109]
	v_mfma_f32_16x16x32_bf16 v[102:105], v[150:153], v[196:199], v[102:105]
	v_mfma_f32_16x16x32_bf16 v[130:133], v[142:145], v[200:203], v[98:101]
	v_mfma_f32_16x16x32_bf16 v[118:121], v[158:161], v[182:185], v[118:121]
	v_mfma_f32_16x16x32_bf16 v[110:113], v[158:161], v[190:193], v[110:113]
	v_mfma_f32_16x16x32_bf16 v[102:105], v[158:161], v[200:203], v[102:105]
	s_barrier
	s_setprio 0
	ds_read_b128 v[98:101], v141
	ds_read_b128 v[154:157], v141 offset:1024
	ds_read_b128 v[204:207], v141 offset:2048
	ds_read_b128 v[138:141], v141 offset:3072
	s_setprio 1
	s_barrier
	s_waitcnt lgkmcnt(0)
	v_mfma_f32_16x16x32_bf16 v[86:89], v[98:101], v[178:181], v[86:89]
	v_mfma_f32_16x16x32_bf16 v[82:85], v[204:207], v[178:181], v[82:85]
	v_mfma_f32_16x16x32_bf16 v[70:73], v[98:101], v[196:199], v[70:73]
	v_mfma_f32_16x16x32_bf16 v[66:69], v[204:207], v[196:199], v[66:69]
	v_mfma_f32_16x16x32_bf16 v[94:97], v[98:101], v[170:173], v[94:97]
	v_mfma_f32_16x16x32_bf16 v[90:93], v[204:207], v[170:173], v[90:93]
	v_mfma_f32_16x16x32_bf16 v[86:89], v[154:157], v[182:185], v[86:89]
	v_mfma_f32_16x16x32_bf16 v[82:85], v[138:141], v[182:185], v[82:85]
	v_mfma_f32_16x16x32_bf16 v[78:81], v[98:101], v[186:189], v[78:81]
	v_mfma_f32_16x16x32_bf16 v[74:77], v[204:207], v[186:189], v[74:77]
	v_mfma_f32_16x16x32_bf16 v[70:73], v[154:157], v[200:203], v[70:73]
	v_mfma_f32_16x16x32_bf16 v[66:69], v[138:141], v[200:203], v[66:69]
	v_mfma_f32_16x16x32_bf16 v[94:97], v[154:157], v[174:177], v[94:97]
	v_mfma_f32_16x16x32_bf16 v[170:173], v[138:141], v[174:177], v[90:93]
	v_mfma_f32_16x16x32_bf16 v[174:177], v[154:157], v[190:193], v[78:81]
	v_mfma_f32_16x16x32_bf16 v[178:181], v[138:141], v[190:193], v[74:77]
	s_barrier
;   #define LDA(dst,b,h) for(int m=0;m<4;++m)for(int k=0;k<2;++k) \
;     dst[m][k]=*reinterpret_cast<const bf16x8*>((char*)SA(b,h)+lds_byte(wr*64+m*16+fr,k*32+fq*8))
;   #define LDB(dst,b,h) for(int n=0;n<2;++n)for(int k=0;k<2;++k) \
;     dst[n][k]=*reinterpret_cast<const bf16x8*>((char*)SB(b,h)+lds_byte(wc*32+n*16+fr,k*32+fq*8))
;   #define MMA(ai,bj,At,Bt_) do{__builtin_amdgcn_s_setprio(1); \
;     for(int m=0;m<4;++m)for(int n=0;n<2;++n)for(int k=0;k<2;++k) \
;       acc[ai][bj][m][n]=__builtin_amdgcn_mfma_f32_16x16x32_bf16(Bt_[n][k],At[m][k],acc[ai][bj][m][n],0,0,0); \
;     __builtin_amdgcn_s_setprio(0);}while(0)
;   #define WAIT_V(n) asm volatile("s_waitcnt vmcnt(" #n ")":::"memory")
;   #define WAIT_L(n) asm volatile("s_waitcnt lgkmcnt(" #n ")":::"memory")
;   #define BAR __builtin_amdgcn_s_barrier()
; template <bool TWO, class MID> ...
;     ...
;   { LDB(B0,0,0); LDA(At,0,0); STAGE_A(SA(1,1),1,nt-1);
;     BAR; WAIT_L(0); MMA(0,0,At,B0); BAR;
;     LDB(B1,0,1); BAR; WAIT_L(0); MMA(0,1,At,B1); BAR;
;     LDA(At,0,1); WAIT_V(4); BAR; WAIT_L(0); MMA(1,0,At,B0); MMA(1,1,At,B1); BAR; }
;   { LDB(B0,1,0); LDA(At,1,0); WAIT_V(2); BAR; WAIT_L(0); MMA(0,0,At,B0); BAR;
;     LDB(B1,1,1); WAIT_V(0); BAR; WAIT_L(0); MMA(0,1,At,B1); BAR;
;     LDA(At,1,1); BAR; WAIT_L(0); MMA(1,0,At,B0); MMA(1,1,At,B1); BAR; }
	s_setprio 0
	s_nop 0
	ds_read_b128 v[74:77], v168 offset:16384
	ds_read_b128 v[78:81], v168 offset:17408
	ds_read_b128 v[90:93], v167 offset:16384
	ds_read_b128 v[182:185], v167 offset:17408
	ds_read_b128 v[186:189], v166 offset:16384
	ds_read_b128 v[190:193], v166 offset:17408
	ds_read_b128 v[196:199], v147 offset:16384
	ds_read_b128 v[200:203], v147 offset:17408
	s_waitcnt vmcnt(4)
	s_setprio 1
	s_barrier
	s_waitcnt lgkmcnt(0)
	v_mfma_f32_16x16x32_bf16 v[62:65], v[150:153], v[74:77], v[62:65]
	v_mfma_f32_16x16x32_bf16 v[58:61], v[162:165], v[74:77], v[58:61]
	v_mfma_f32_16x16x32_bf16 v[54:57], v[150:153], v[90:93], v[54:57]
	v_mfma_f32_16x16x32_bf16 v[50:53], v[162:165], v[90:93], v[50:53]
	v_mfma_f32_16x16x32_bf16 v[38:41], v[150:153], v[196:199], v[38:41]
	v_mfma_f32_16x16x32_bf16 v[34:37], v[162:165], v[196:199], v[34:37]
	v_mfma_f32_16x16x32_bf16 v[62:65], v[158:161], v[78:81], v[62:65]
	v_mfma_f32_16x16x32_bf16 v[58:61], v[142:145], v[78:81], v[58:61]
	v_mfma_f32_16x16x32_bf16 v[54:57], v[158:161], v[182:185], v[54:57]
	v_mfma_f32_16x16x32_bf16 v[50:53], v[142:145], v[182:185], v[50:53]
	v_mfma_f32_16x16x32_bf16 v[46:49], v[150:153], v[186:189], v[46:49]
	v_mfma_f32_16x16x32_bf16 v[42:45], v[162:165], v[186:189], v[42:45]
	v_mfma_f32_16x16x32_bf16 v[38:41], v[158:161], v[200:203], v[38:41]
	v_mfma_f32_16x16x32_bf16 v[34:37], v[142:145], v[200:203], v[34:37]
	v_mfma_f32_16x16x32_bf16 v[208:211], v[158:161], v[190:193], v[46:49]
	v_mfma_f32_16x16x32_bf16 v[212:215], v[142:145], v[190:193], v[42:45]
	s_setprio 0
	s_setprio 1
	v_mfma_f32_16x16x32_bf16 v[22:25], v[98:101], v[90:93], v[22:25]
	v_mfma_f32_16x16x32_bf16 v[18:21], v[204:207], v[90:93], v[18:21]
	v_mfma_f32_16x16x32_bf16 v[6:9], v[98:101], v[196:199], v[6:9]
	v_mfma_f32_16x16x32_bf16 v[2:5], v[204:207], v[196:199], v[2:5]
	v_mfma_f32_16x16x32_bf16 v[30:33], v[98:101], v[74:77], v[30:33]
	v_mfma_f32_16x16x32_bf16 v[26:29], v[204:207], v[74:77], v[26:29]
	v_mfma_f32_16x16x32_bf16 v[22:25], v[154:157], v[182:185], v[22:25]
	v_mfma_f32_16x16x32_bf16 v[18:21], v[138:141], v[182:185], v[18:21]
	v_mfma_f32_16x16x32_bf16 v[14:17], v[98:101], v[186:189], v[14:17]
	v_mfma_f32_16x16x32_bf16 v[10:13], v[204:207], v[186:189], v[10:13]
	v_mfma_f32_16x16x32_bf16 v[6:9], v[154:157], v[200:203], v[6:9]
	v_mfma_f32_16x16x32_bf16 v[2:5], v[138:141], v[200:203], v[2:5]
	v_mfma_f32_16x16x32_bf16 v[148:151], v[154:157], v[78:81], v[30:33]
	v_mfma_f32_16x16x32_bf16 v[158:161], v[138:141], v[78:81], v[26:29]
	v_mfma_f32_16x16x32_bf16 v[162:165], v[154:157], v[190:193], v[14:17]
	v_mfma_f32_16x16x32_bf16 v[182:185], v[138:141], v[190:193], v[10:13]
	s_barrier
	s_setprio 0
	s_nop 0
	ds_read_b128 v[10:13], v137
	ds_read_b128 v[14:17], v137 offset:1024
	ds_read_b128 v[152:155], v137 offset:2048
	ds_read_b128 v[186:189], v137 offset:3072
	ds_read_b128 v[26:29], v168 offset:32768
	ds_read_b128 v[30:33], v168 offset:33792
	ds_read_b128 v[42:45], v167 offset:32768
	ds_read_b128 v[46:49], v167 offset:33792
	ds_read_b128 v[190:193], v166 offset:32768
	ds_read_b128 v[196:199], v166 offset:33792
	ds_read_b128 v[200:203], v147 offset:32768
	ds_read_b128 v[204:207], v147 offset:33792
	s_waitcnt vmcnt(2)
	s_setprio 1
	s_barrier
	s_waitcnt lgkmcnt(0)
	v_mfma_f32_16x16x32_bf16 v[74:77], v[10:13], v[26:29], v[126:129]
	v_mfma_f32_16x16x32_bf16 v[142:145], v[14:17], v[30:33], v[74:77]
	v_mfma_f32_16x16x32_bf16 v[74:77], v[152:155], v[26:29], v[122:125]
	v_mfma_f32_16x16x32_bf16 v[138:141], v[186:189], v[30:33], v[74:77]
	v_mfma_f32_16x16x32_bf16 v[74:77], v[10:13], v[42:45], v[118:121]
	v_mfma_f32_16x16x32_bf16 v[126:129], v[14:17], v[46:49], v[74:77]
	v_mfma_f32_16x16x32_bf16 v[74:77], v[152:155], v[42:45], v[114:117]
	v_mfma_f32_16x16x32_bf16 v[122:125], v[186:189], v[46:49], v[74:77]
	v_mfma_f32_16x16x32_bf16 v[74:77], v[10:13], v[190:193], v[110:113]
	v_mfma_f32_16x16x32_bf16 v[98:101], v[14:17], v[196:199], v[74:77]
	v_mfma_f32_16x16x32_bf16 v[74:77], v[152:155], v[190:193], v[106:109]
	v_mfma_f32_16x16x32_bf16 v[90:93], v[186:189], v[196:199], v[74:77]
	v_mfma_f32_16x16x32_bf16 v[74:77], v[10:13], v[200:203], v[102:105]
	v_mfma_f32_16x16x32_bf16 v[78:81], v[14:17], v[204:207], v[74:77]
	v_mfma_f32_16x16x32_bf16 v[74:77], v[152:155], v[200:203], v[130:133]
	v_mfma_f32_16x16x32_bf16 v[74:77], v[186:189], v[204:207], v[74:77]
	s_barrier
;   #define LDA(dst,b,h) for(int m=0;m<4;++m)for(int k=0;k<2;++k) \
;     dst[m][k]=*reinterpret_cast<const bf16x8*>((char*)SA(b,h)+lds_byte(wr*64+m*16+fr,k*32+fq*8))
;   #define LDB(dst,b,h) for(int n=0;n<2;++n)for(int k=0;k<2;++k) \
;     dst[n][k]=*reinterpret_cast<const bf16x8*>((char*)SB(b,h)+lds_byte(wc*32+n*16+fr,k*32+fq*8))
;   #define MMA(ai,bj,At,Bt_) do{__builtin_amdgcn_s_setprio(1); \
;     for(int m=0;m<4;++m)for(int n=0;n<2;++n)for(int k=0;k<2;++k) \
;       acc[ai][bj][m][n]=__builtin_amdgcn_mfma_f32_16x16x32_bf16(Bt_[n][k],At[m][k],acc[ai][bj][m][n],0,0,0); \
;     __builtin_amdgcn_s_setprio(0);}while(0)
;   #define WAIT_V(n) asm volatile("s_waitcnt vmcnt(" #n ")":::"memory")
;   #define WAIT_L(n) asm volatile("s_waitcnt lgkmcnt(" #n ")":::"memory")
;   #define BAR __builtin_amdgcn_s_barrier()
; template <bool TWO, class MID> ...
;     ...
;   { LDB(B0,1,0); LDA(At,1,0); WAIT_V(2); BAR; WAIT_L(0); MMA(0,0,At,B0); BAR;
;     LDB(B1,1,1); WAIT_V(0); BAR; WAIT_L(0); MMA(0,1,At,B1); BAR;
;     LDA(At,1,1); BAR; WAIT_L(0); MMA(1,0,At,B0); MMA(1,1,At,B1); BAR; }
;   if(wr==0)BAR;
	s_setprio 0
	ds_read_b128 v[102:105], v135
	ds_read_b128 v[110:113], v135 offset:1024
	ds_read_b128 v[118:121], v135 offset:2048
	ds_read_b128 v[216:219], v135 offset:3072
	s_waitcnt vmcnt(0)
	s_setprio 1
	s_barrier
	s_waitcnt lgkmcnt(0)
	v_mfma_f32_16x16x32_bf16 v[94:97], v[102:105], v[26:29], v[94:97]
	v_mfma_f32_16x16x32_bf16 v[26:29], v[118:121], v[26:29], v[170:173]
	v_mfma_f32_16x16x32_bf16 v[130:133], v[216:219], v[30:33], v[26:29]
	v_mfma_f32_16x16x32_bf16 v[26:29], v[102:105], v[42:45], v[86:89]
	v_mfma_f32_16x16x32_bf16 v[114:117], v[110:113], v[46:49], v[26:29]
	v_mfma_f32_16x16x32_bf16 v[26:29], v[118:121], v[42:45], v[82:85]
	v_mfma_f32_16x16x32_bf16 v[106:109], v[216:219], v[46:49], v[26:29]
	v_mfma_f32_16x16x32_bf16 v[26:29], v[102:105], v[190:193], v[174:177]
	v_mfma_f32_16x16x32_bf16 v[86:89], v[110:113], v[196:199], v[26:29]
	v_mfma_f32_16x16x32_bf16 v[26:29], v[118:121], v[190:193], v[178:181]
	v_mfma_f32_16x16x32_bf16 v[82:85], v[216:219], v[196:199], v[26:29]
	v_mfma_f32_16x16x32_bf16 v[26:29], v[102:105], v[200:203], v[70:73]
	v_mfma_f32_16x16x32_bf16 v[70:73], v[110:113], v[204:207], v[26:29]
	v_mfma_f32_16x16x32_bf16 v[26:29], v[118:121], v[200:203], v[66:69]
	v_mfma_f32_16x16x32_bf16 v[134:137], v[110:113], v[30:33], v[94:97]
	v_mfma_f32_16x16x32_bf16 v[66:69], v[216:219], v[204:207], v[26:29]
	s_barrier
	s_setprio 0
	ds_read_b128 v[94:97], v168 offset:49152
	ds_read_b128 v[168:171], v168 offset:50176
	ds_read_b128 v[172:175], v167 offset:49152
	ds_read_b128 v[176:179], v167 offset:50176
	ds_read_b128 v[190:193], v166 offset:49152
	ds_read_b128 v[196:199], v166 offset:50176
	ds_read_b128 v[200:203], v147 offset:49152
	ds_read_b128 v[204:207], v147 offset:50176
	s_setprio 1
	s_barrier
	s_waitcnt lgkmcnt(0)
	v_mfma_f32_16x16x32_bf16 v[26:29], v[10:13], v[94:97], v[62:65]
	v_mfma_f32_16x16x32_bf16 v[62:65], v[14:17], v[168:171], v[26:29]
	v_mfma_f32_16x16x32_bf16 v[26:29], v[152:155], v[94:97], v[58:61]
	v_mfma_f32_16x16x32_bf16 v[58:61], v[186:189], v[168:171], v[26:29]
	v_mfma_f32_16x16x32_bf16 v[26:29], v[10:13], v[172:175], v[54:57]
	v_mfma_f32_16x16x32_bf16 v[46:49], v[14:17], v[176:179], v[26:29]
	v_mfma_f32_16x16x32_bf16 v[26:29], v[152:155], v[172:175], v[50:53]
	v_mfma_f32_16x16x32_bf16 v[42:45], v[186:189], v[176:179], v[26:29]
	v_mfma_f32_16x16x32_bf16 v[26:29], v[10:13], v[190:193], v[208:211]
	v_mfma_f32_16x16x32_bf16 v[10:13], v[10:13], v[200:203], v[38:41]
	v_mfma_f32_16x16x32_bf16 v[30:33], v[14:17], v[196:199], v[26:29]
	v_mfma_f32_16x16x32_bf16 v[26:29], v[152:155], v[190:193], v[212:215]
	v_mfma_f32_16x16x32_bf16 v[14:17], v[14:17], v[204:207], v[10:13]
	v_mfma_f32_16x16x32_bf16 v[10:13], v[152:155], v[200:203], v[34:37]
	v_mfma_f32_16x16x32_bf16 v[26:29], v[186:189], v[196:199], v[26:29]
	v_mfma_f32_16x16x32_bf16 v[10:13], v[186:189], v[204:207], v[10:13]
	s_setprio 0
	s_setprio 1
	v_mfma_f32_16x16x32_bf16 v[34:37], v[102:105], v[94:97], v[148:151]
	v_mfma_f32_16x16x32_bf16 v[54:57], v[110:113], v[168:171], v[34:37]
	v_mfma_f32_16x16x32_bf16 v[34:37], v[118:121], v[94:97], v[158:161]
	v_mfma_f32_16x16x32_bf16 v[18:21], v[118:121], v[172:175], v[18:21]
	v_mfma_f32_16x16x32_bf16 v[50:53], v[216:219], v[168:171], v[34:37]
	v_mfma_f32_16x16x32_bf16 v[22:25], v[102:105], v[172:175], v[22:25]
	v_mfma_f32_16x16x32_bf16 v[34:37], v[216:219], v[176:179], v[18:21]
	v_mfma_f32_16x16x32_bf16 v[18:21], v[102:105], v[190:193], v[162:165]
	v_mfma_f32_16x16x32_bf16 v[38:41], v[110:113], v[176:179], v[22:25]
	v_mfma_f32_16x16x32_bf16 v[22:25], v[110:113], v[196:199], v[18:21]
	v_mfma_f32_16x16x32_bf16 v[18:21], v[118:121], v[190:193], v[182:185]
	v_mfma_f32_16x16x32_bf16 v[6:9], v[102:105], v[200:203], v[6:9]
	v_mfma_f32_16x16x32_bf16 v[2:5], v[118:121], v[200:203], v[2:5]
	v_mfma_f32_16x16x32_bf16 v[18:21], v[216:219], v[196:199], v[18:21]
	v_mfma_f32_16x16x32_bf16 v[6:9], v[110:113], v[204:207], v[6:9]
	v_mfma_f32_16x16x32_bf16 v[2:5], v[216:219], v[204:207], v[2:5]
	s_setprio 0
	v_cmp_gt_u32_e32 vcc, s30, v1
	s_barrier
	s_and_saveexec_b64 s[0:1], vcc
	s_cbranch_execz .LBB0_172
	s_barrier

;   #define LDA(dst,b,h) for(int m=0;m<4;++m)for(int k=0;k<2;++k) \
;     dst[m][k]=*reinterpret_cast<const bf16x8*>((char*)SA(b,h)+lds_byte(wr*64+m*16+fr,k*32+fq*8))
;   #define LDB(dst,b,h) for(int n=0;n<2;++n)for(int k=0;k<2;++k) \
;     dst[n][k]=*reinterpret_cast<const bf16x8*>((char*)SB(b,h)+lds_byte(wc*32+n*16+fr,k*32+fq*8))
;   #define MMA(ai,bj,At,Bt_) do{__builtin_amdgcn_s_setprio(1); \
;     for(int m=0;m<4;++m)for(int n=0;n<2;++n)for(int k=0;k<2;++k) \
;       acc[ai][bj][m][n]=__builtin_amdgcn_mfma_f32_16x16x32_bf16(Bt_[n][k],At[m][k],acc[ai][bj][m][n],0,0,0); \
;     __builtin_amdgcn_s_setprio(0);}while(0)
;   #define WAIT_V(n) asm volatile("s_waitcnt vmcnt(" #n ")":::"memory")
;   #define WAIT_L(n) asm volatile("s_waitcnt lgkmcnt(" #n ")":::"memory")
;   #define BAR __builtin_amdgcn_s_barrier()
;   #define SCHED __builtin_amdgcn_sched_barrier(0)
; template <bool TWO, class MID> ...
;     ...
;     LDB(B0,0,0); SCHED; LDA(At,0,0); STAGE_A(SA(1,1),1,t+1);
;     WAIT_L(8); BAR; WAIT_L(0); MMA(0,0,At,B0); BAR; SCHED;
;     LDB(B1,0,1); STAGE_B(SB(0,0),0,t+2);
;     BAR; WAIT_L(0); MMA(0,1,At,B1); BAR;
;     LDA(At,0,1); STAGE_A(SA(0,0),0,t+2);
;     BAR; WAIT_L(0); MMA(1,0,At,B0); BAR; SCHED;
;     STAGE_B(SB(0,1),1,t+2);
;     WAIT_V(6); BAR; MMA(1,1,At,B1); BAR;
.LBB0_489:
	ds_read_b128 v[166:169], v149
	ds_read_b128 v[170:173], v149 offset:1024
	ds_read_b128 v[174:177], v149 offset:2048
	ds_read_b128 v[178:181], v149 offset:3072
	ds_read_b128 v[182:185], v141
	ds_read_b128 v[186:189], v141 offset:1024
	ds_read_b128 v[190:193], v139
	ds_read_b128 v[196:199], v139 offset:1024
	ds_read_b128 v[200:203], v137
	ds_read_b128 v[204:207], v137 offset:1024
	ds_read_b128 v[208:211], v135
	ds_read_b128 v[212:215], v135 offset:1024
	s_add_u32 s19, s4, s10
	s_addc_u32 s24, s5, s11
	s_add_u32 m0, s98, 0xc000
	s_add_u32 s26, s19, 0x36080080
	s_addc_u32 s27, s24, 0
	global_load_lds_dwordx4 v132, s[26:27]
	s_add_u32 m0, s98, 0xe000
	s_setprio 1
	global_load_lds_dwordx4 v130, s[26:27]
	s_waitcnt lgkmcnt(8)
	s_barrier
	s_waitcnt lgkmcnt(0)
	v_mfma_f32_16x16x32_bf16 v[126:129], v[166:169], v[182:185], v[126:129]
	v_mfma_f32_16x16x32_bf16 v[122:125], v[174:177], v[182:185], v[122:125]
	v_mfma_f32_16x16x32_bf16 v[118:121], v[166:169], v[190:193], v[118:121]
	v_mfma_f32_16x16x32_bf16 v[114:117], v[174:177], v[190:193], v[114:117]
	v_mfma_f32_16x16x32_bf16 v[110:113], v[166:169], v[200:203], v[110:113]
	v_mfma_f32_16x16x32_bf16 v[106:109], v[174:177], v[200:203], v[106:109]
	v_mfma_f32_16x16x32_bf16 v[102:105], v[166:169], v[208:211], v[102:105]
	v_mfma_f32_16x16x32_bf16 v[98:101], v[174:177], v[208:211], v[98:101]
	v_mfma_f32_16x16x32_bf16 v[126:129], v[170:173], v[186:189], v[126:129]
	v_mfma_f32_16x16x32_bf16 v[122:125], v[178:181], v[186:189], v[122:125]
	v_mfma_f32_16x16x32_bf16 v[118:121], v[170:173], v[196:199], v[118:121]
	v_mfma_f32_16x16x32_bf16 v[114:117], v[178:181], v[196:199], v[114:117]
	v_mfma_f32_16x16x32_bf16 v[110:113], v[170:173], v[204:207], v[110:113]
	v_mfma_f32_16x16x32_bf16 v[106:109], v[178:181], v[204:207], v[106:109]
	v_mfma_f32_16x16x32_bf16 v[102:105], v[170:173], v[212:215], v[102:105]
	v_mfma_f32_16x16x32_bf16 v[98:101], v[178:181], v[212:215], v[98:101]
	s_barrier
	s_setprio 0
	s_add_u32 s25, s4, s16
	ds_read_b128 v[216:219], v147
	ds_read_b128 v[220:223], v147 offset:1024
	ds_read_b128 v[224:227], v147 offset:2048
	ds_read_b128 v[228:231], v147 offset:3072
	s_addc_u32 s26, s5, s17
	s_add_u32 m0, s98, 0x10000
	s_add_u32 s28, s25, 0x3400100
	s_addc_u32 s29, s26, 0
	global_load_lds_dwordx4 v132, s[28:29]
	s_add_u32 m0, s98, 0x12000
	s_setprio 1
	global_load_lds_dwordx4 v130, s[28:29]
	s_barrier
	s_waitcnt lgkmcnt(0)
	v_mfma_f32_16x16x32_bf16 v[94:97], v[216:219], v[182:185], v[94:97]
	v_mfma_f32_16x16x32_bf16 v[90:93], v[224:227], v[182:185], v[90:93]
	v_mfma_f32_16x16x32_bf16 v[86:89], v[216:219], v[190:193], v[86:89]
	v_mfma_f32_16x16x32_bf16 v[82:85], v[224:227], v[190:193], v[82:85]
	v_mfma_f32_16x16x32_bf16 v[78:81], v[216:219], v[200:203], v[78:81]
	v_mfma_f32_16x16x32_bf16 v[74:77], v[224:227], v[200:203], v[74:77]
	v_mfma_f32_16x16x32_bf16 v[70:73], v[216:219], v[208:211], v[70:73]
	v_mfma_f32_16x16x32_bf16 v[66:69], v[224:227], v[208:211], v[66:69]
	v_mfma_f32_16x16x32_bf16 v[94:97], v[220:223], v[186:189], v[94:97]
	v_mfma_f32_16x16x32_bf16 v[90:93], v[228:231], v[186:189], v[90:93]
	v_mfma_f32_16x16x32_bf16 v[86:89], v[220:223], v[196:199], v[86:89]
	v_mfma_f32_16x16x32_bf16 v[82:85], v[228:231], v[196:199], v[82:85]
	v_mfma_f32_16x16x32_bf16 v[78:81], v[220:223], v[204:207], v[78:81]
	v_mfma_f32_16x16x32_bf16 v[74:77], v[228:231], v[204:207], v[74:77]
	v_mfma_f32_16x16x32_bf16 v[70:73], v[220:223], v[212:215], v[70:73]
	v_mfma_f32_16x16x32_bf16 v[66:69], v[228:231], v[212:215], v[66:69]
	s_barrier
	s_setprio 0
	ds_read_b128 v[182:185], v141 offset:16384
	ds_read_b128 v[186:189], v141 offset:17408
	ds_read_b128 v[190:193], v139 offset:16384
	ds_read_b128 v[196:199], v139 offset:17408
	ds_read_b128 v[200:203], v137 offset:16384
	ds_read_b128 v[204:207], v137 offset:17408
	ds_read_b128 v[208:211], v135 offset:16384
	ds_read_b128 v[212:215], v135 offset:17408
	s_add_u32 m0, s98, 0x0
	s_add_u32 s28, s19, 0x36000100
	s_addc_u32 s29, s24, 0
	global_load_lds_dwordx4 v132, s[28:29]
	s_add_u32 m0, s98, 0x2000
	s_setprio 1
	global_load_lds_dwordx4 v130, s[28:29]
	s_barrier
	s_waitcnt lgkmcnt(0)
	v_mfma_f32_16x16x32_bf16 v[62:65], v[166:169], v[182:185], v[62:65]
	v_mfma_f32_16x16x32_bf16 v[58:61], v[174:177], v[182:185], v[58:61]
	v_mfma_f32_16x16x32_bf16 v[54:57], v[166:169], v[190:193], v[54:57]
	v_mfma_f32_16x16x32_bf16 v[50:53], v[174:177], v[190:193], v[50:53]
	v_mfma_f32_16x16x32_bf16 v[46:49], v[166:169], v[200:203], v[46:49]
	v_mfma_f32_16x16x32_bf16 v[42:45], v[174:177], v[200:203], v[42:45]
	v_mfma_f32_16x16x32_bf16 v[38:41], v[166:169], v[208:211], v[38:41]
	v_mfma_f32_16x16x32_bf16 v[34:37], v[174:177], v[208:211], v[34:37]
	v_mfma_f32_16x16x32_bf16 v[62:65], v[170:173], v[186:189], v[62:65]
	v_mfma_f32_16x16x32_bf16 v[58:61], v[178:181], v[186:189], v[58:61]
	v_mfma_f32_16x16x32_bf16 v[54:57], v[170:173], v[196:199], v[54:57]
	v_mfma_f32_16x16x32_bf16 v[50:53], v[178:181], v[196:199], v[50:53]
	v_mfma_f32_16x16x32_bf16 v[46:49], v[170:173], v[204:207], v[46:49]
	v_mfma_f32_16x16x32_bf16 v[42:45], v[178:181], v[204:207], v[42:45]
	v_mfma_f32_16x16x32_bf16 v[38:41], v[170:173], v[212:215], v[38:41]
	v_mfma_f32_16x16x32_bf16 v[34:37], v[178:181], v[212:215], v[34:37]
	s_barrier
	s_setprio 0
	s_add_u32 m0, s98, 0x14000
	s_add_u32 s28, s25, 0x3480100
	s_addc_u32 s29, s26, 0
	global_load_lds_dwordx4 v132, s[28:29]
	s_add_u32 m0, s98, 0x16000
	s_setprio 1
	global_load_lds_dwordx4 v130, s[28:29]
	s_waitcnt vmcnt(6)
	s_barrier
;   #define LDA(dst,b,h) for(int m=0;m<4;++m)for(int k=0;k<2;++k) \
;     dst[m][k]=*reinterpret_cast<const bf16x8*>((char*)SA(b,h)+lds_byte(wr*64+m*16+fr,k*32+fq*8))
;   #define LDB(dst,b,h) for(int n=0;n<2;++n)for(int k=0;k<2;++k) \
;     dst[n][k]=*reinterpret_cast<const bf16x8*>((char*)SB(b,h)+lds_byte(wc*32+n*16+fr,k*32+fq*8))
;   #define MMA(ai,bj,At,Bt_) do{__builtin_amdgcn_s_setprio(1); \
;     for(int m=0;m<4;++m)for(int n=0;n<2;++n)for(int k=0;k<2;++k) \
;       acc[ai][bj][m][n]=__builtin_amdgcn_mfma_f32_16x16x32_bf16(Bt_[n][k],At[m][k],acc[ai][bj][m][n],0,0,0); \
;     __builtin_amdgcn_s_setprio(0);}while(0)
;   #define WAIT_V(n) asm volatile("s_waitcnt vmcnt(" #n ")":::"memory")
;   #define WAIT_L(n) asm volatile("s_waitcnt lgkmcnt(" #n ")":::"memory")
;   #define BAR __builtin_amdgcn_s_barrier()
;   #define SCHED __builtin_amdgcn_sched_barrier(0)
; template <bool TWO, class MID> ...
;     ...
;     WAIT_V(6); BAR; MMA(1,1,At,B1); BAR;
;     LDB(B0,1,0); SCHED; LDA(At,1,0); STAGE_A(SA(0,1),1,t+2);
;     WAIT_L(8); BAR; WAIT_L(0); MMA(0,0,At,B0); BAR; SCHED;
;     LDB(B1,1,1); STAGE_B(SB(1,0),0,t+3);
;     BAR; WAIT_L(0); MMA(0,1,At,B1); BAR;
;     LDA(At,1,1); STAGE_A(SA(1,0),0,t+3);
	v_mfma_f32_16x16x32_bf16 v[30:33], v[216:219], v[182:185], v[30:33]
	v_mfma_f32_16x16x32_bf16 v[26:29], v[224:227], v[182:185], v[26:29]
	v_mfma_f32_16x16x32_bf16 v[22:25], v[216:219], v[190:193], v[22:25]
	v_mfma_f32_16x16x32_bf16 v[18:21], v[224:227], v[190:193], v[18:21]
	v_mfma_f32_16x16x32_bf16 v[14:17], v[216:219], v[200:203], v[14:17]
	v_mfma_f32_16x16x32_bf16 v[10:13], v[224:227], v[200:203], v[10:13]
	v_mfma_f32_16x16x32_bf16 v[6:9], v[216:219], v[208:211], v[6:9]
	v_mfma_f32_16x16x32_bf16 v[2:5], v[224:227], v[208:211], v[2:5]
	v_mfma_f32_16x16x32_bf16 v[30:33], v[220:223], v[186:189], v[30:33]
	v_mfma_f32_16x16x32_bf16 v[26:29], v[228:231], v[186:189], v[26:29]
	v_mfma_f32_16x16x32_bf16 v[22:25], v[220:223], v[196:199], v[22:25]
	v_mfma_f32_16x16x32_bf16 v[18:21], v[228:231], v[196:199], v[18:21]
	v_mfma_f32_16x16x32_bf16 v[14:17], v[220:223], v[204:207], v[14:17]
	v_mfma_f32_16x16x32_bf16 v[10:13], v[228:231], v[204:207], v[10:13]
	v_mfma_f32_16x16x32_bf16 v[6:9], v[220:223], v[212:215], v[6:9]
	v_mfma_f32_16x16x32_bf16 v[2:5], v[228:231], v[212:215], v[2:5]
	s_barrier
	s_setprio 0
	ds_read_b128 v[166:169], v145
	ds_read_b128 v[170:173], v145 offset:1024
	ds_read_b128 v[174:177], v145 offset:2048
	ds_read_b128 v[178:181], v145 offset:3072
	ds_read_b128 v[182:185], v141 offset:32768
	ds_read_b128 v[186:189], v141 offset:33792
	ds_read_b128 v[190:193], v139 offset:32768
	ds_read_b128 v[196:199], v139 offset:33792
	ds_read_b128 v[200:203], v137 offset:32768
	ds_read_b128 v[204:207], v137 offset:33792
	ds_read_b128 v[208:211], v135 offset:32768
	ds_read_b128 v[212:215], v135 offset:33792
	s_add_u32 m0, s98, 0x4000
	s_add_u32 s28, s19, 0x36080100
	s_addc_u32 s29, s24, 0
	global_load_lds_dwordx4 v132, s[28:29]
	s_add_u32 m0, s98, 0x6000
	s_setprio 1
	global_load_lds_dwordx4 v130, s[28:29]
	s_waitcnt lgkmcnt(8)
	s_barrier
	s_waitcnt lgkmcnt(0)
	v_mfma_f32_16x16x32_bf16 v[126:129], v[166:169], v[182:185], v[126:129]
	v_mfma_f32_16x16x32_bf16 v[122:125], v[174:177], v[182:185], v[122:125]
	v_mfma_f32_16x16x32_bf16 v[118:121], v[166:169], v[190:193], v[118:121]
	v_mfma_f32_16x16x32_bf16 v[114:117], v[174:177], v[190:193], v[114:117]
	v_mfma_f32_16x16x32_bf16 v[110:113], v[166:169], v[200:203], v[110:113]
	v_mfma_f32_16x16x32_bf16 v[106:109], v[174:177], v[200:203], v[106:109]
	v_mfma_f32_16x16x32_bf16 v[102:105], v[166:169], v[208:211], v[102:105]
	v_mfma_f32_16x16x32_bf16 v[98:101], v[174:177], v[208:211], v[98:101]
	v_mfma_f32_16x16x32_bf16 v[126:129], v[170:173], v[186:189], v[126:129]
	v_mfma_f32_16x16x32_bf16 v[122:125], v[178:181], v[186:189], v[122:125]
	v_mfma_f32_16x16x32_bf16 v[118:121], v[170:173], v[196:199], v[118:121]
	v_mfma_f32_16x16x32_bf16 v[114:117], v[178:181], v[196:199], v[114:117]
	v_mfma_f32_16x16x32_bf16 v[110:113], v[170:173], v[204:207], v[110:113]
	v_mfma_f32_16x16x32_bf16 v[106:109], v[178:181], v[204:207], v[106:109]
	v_mfma_f32_16x16x32_bf16 v[102:105], v[170:173], v[212:215], v[102:105]
	v_mfma_f32_16x16x32_bf16 v[98:101], v[178:181], v[212:215], v[98:101]
	s_barrier
	s_setprio 0
	ds_read_b128 v[216:219], v143
	ds_read_b128 v[220:223], v143 offset:1024
	ds_read_b128 v[224:227], v143 offset:2048
	ds_read_b128 v[228:231], v143 offset:3072
	s_add_u32 m0, s98, 0x18000
	s_add_u32 s28, s25, 0x3400180
	s_addc_u32 s29, s26, 0
	global_load_lds_dwordx4 v132, s[28:29]
	s_add_u32 m0, s98, 0x1a000
	s_setprio 1
	global_load_lds_dwordx4 v130, s[28:29]
	s_barrier
	s_waitcnt lgkmcnt(0)
	v_mfma_f32_16x16x32_bf16 v[94:97], v[216:219], v[182:185], v[94:97]
	v_mfma_f32_16x16x32_bf16 v[90:93], v[224:227], v[182:185], v[90:93]
	v_mfma_f32_16x16x32_bf16 v[86:89], v[216:219], v[190:193], v[86:89]
	v_mfma_f32_16x16x32_bf16 v[82:85], v[224:227], v[190:193], v[82:85]
	v_mfma_f32_16x16x32_bf16 v[78:81], v[216:219], v[200:203], v[78:81]
	v_mfma_f32_16x16x32_bf16 v[74:77], v[224:227], v[200:203], v[74:77]
	v_mfma_f32_16x16x32_bf16 v[70:73], v[216:219], v[208:211], v[70:73]
	v_mfma_f32_16x16x32_bf16 v[66:69], v[224:227], v[208:211], v[66:69]
	v_mfma_f32_16x16x32_bf16 v[94:97], v[220:223], v[186:189], v[94:97]
	v_mfma_f32_16x16x32_bf16 v[90:93], v[228:231], v[186:189], v[90:93]
	v_mfma_f32_16x16x32_bf16 v[86:89], v[220:223], v[196:199], v[86:89]
	v_mfma_f32_16x16x32_bf16 v[82:85], v[228:231], v[196:199], v[82:85]
	v_mfma_f32_16x16x32_bf16 v[78:81], v[220:223], v[204:207], v[78:81]
	v_mfma_f32_16x16x32_bf16 v[74:77], v[228:231], v[204:207], v[74:77]
	v_mfma_f32_16x16x32_bf16 v[70:73], v[220:223], v[212:215], v[70:73]
	v_mfma_f32_16x16x32_bf16 v[66:69], v[228:231], v[212:215], v[66:69]
	s_barrier
	s_setprio 0
	ds_read_b128 v[182:185], v141 offset:49152
	ds_read_b128 v[186:189], v141 offset:50176
	ds_read_b128 v[190:193], v139 offset:49152
	ds_read_b128 v[196:199], v139 offset:50176
	ds_read_b128 v[200:203], v137 offset:49152
	ds_read_b128 v[204:207], v137 offset:50176
	ds_read_b128 v[208:211], v135 offset:49152
	ds_read_b128 v[212:215], v135 offset:50176
	s_add_u32 m0, s98, 0x8000
	s_add_u32 s28, s19, 0x36000180
	s_addc_u32 s29, s24, 0
	global_load_lds_dwordx4 v132, s[28:29]
	s_add_u32 m0, s98, 0xa000
	s_setprio 1
	global_load_lds_dwordx4 v130, s[28:29]
	s_barrier
;   #define LDA(dst,b,h) for(int m=0;m<4;++m)for(int k=0;k<2;++k) \
;     dst[m][k]=*reinterpret_cast<const bf16x8*>((char*)SA(b,h)+lds_byte(wr*64+m*16+fr,k*32+fq*8))
;   #define LDB(dst,b,h) for(int n=0;n<2;++n)for(int k=0;k<2;++k) \
;     dst[n][k]=*reinterpret_cast<const bf16x8*>((char*)SB(b,h)+lds_byte(wc*32+n*16+fr,k*32+fq*8))
;   #define MMA(ai,bj,At,Bt_) do{__builtin_amdgcn_s_setprio(1); \
;     for(int m=0;m<4;++m)for(int n=0;n<2;++n)for(int k=0;k<2;++k) \
;       acc[ai][bj][m][n]=__builtin_amdgcn_mfma_f32_16x16x32_bf16(Bt_[n][k],At[m][k],acc[ai][bj][m][n],0,0,0); \
;     __builtin_amdgcn_s_setprio(0);}while(0)
;   #define WAIT_V(n) asm volatile("s_waitcnt vmcnt(" #n ")":::"memory")
;   #define WAIT_L(n) asm volatile("s_waitcnt lgkmcnt(" #n ")":::"memory")
;   #define BAR __builtin_amdgcn_s_barrier()
;   #define SCHED __builtin_amdgcn_sched_barrier(0)
; template <bool TWO, class MID> ...
;     ...
;     LDA(At,1,1); STAGE_A(SA(1,0),0,t+3);
;     BAR; WAIT_L(0); MMA(1,0,At,B0); BAR; SCHED;
;     STAGE_B(SB(1,1),1,t+3);
;     WAIT_V(6); BAR; MMA(1,1,At,B1); BAR;
;   }
;   { LDB(B0,0,0); LDA(At,0,0); STAGE_A(SA(1,1),1,nt-1);
;     BAR; WAIT_L(0); MMA(0,0,At,B0); BAR;
;     LDB(B1,0,1); BAR; WAIT_L(0); MMA(0,1,At,B1); BAR;
	s_waitcnt lgkmcnt(0)
	v_mfma_f32_16x16x32_bf16 v[62:65], v[166:169], v[182:185], v[62:65]
	v_mfma_f32_16x16x32_bf16 v[58:61], v[174:177], v[182:185], v[58:61]
	v_mfma_f32_16x16x32_bf16 v[54:57], v[166:169], v[190:193], v[54:57]
	v_mfma_f32_16x16x32_bf16 v[50:53], v[174:177], v[190:193], v[50:53]
	v_mfma_f32_16x16x32_bf16 v[46:49], v[166:169], v[200:203], v[46:49]
	v_mfma_f32_16x16x32_bf16 v[42:45], v[174:177], v[200:203], v[42:45]
	v_mfma_f32_16x16x32_bf16 v[38:41], v[166:169], v[208:211], v[38:41]
	v_mfma_f32_16x16x32_bf16 v[34:37], v[174:177], v[208:211], v[34:37]
	v_mfma_f32_16x16x32_bf16 v[62:65], v[170:173], v[186:189], v[62:65]
	v_mfma_f32_16x16x32_bf16 v[58:61], v[178:181], v[186:189], v[58:61]
	v_mfma_f32_16x16x32_bf16 v[54:57], v[170:173], v[196:199], v[54:57]
	v_mfma_f32_16x16x32_bf16 v[50:53], v[178:181], v[196:199], v[50:53]
	v_mfma_f32_16x16x32_bf16 v[46:49], v[170:173], v[204:207], v[46:49]
	v_mfma_f32_16x16x32_bf16 v[42:45], v[178:181], v[204:207], v[42:45]
	v_mfma_f32_16x16x32_bf16 v[38:41], v[170:173], v[212:215], v[38:41]
	v_mfma_f32_16x16x32_bf16 v[34:37], v[178:181], v[212:215], v[34:37]
	s_barrier
	s_setprio 0
	s_add_u32 m0, s98, 0x1c000
	s_add_u32 s24, s25, 0x3480180
	s_addc_u32 s25, s26, 0
	global_load_lds_dwordx4 v132, s[24:25]
	s_add_u32 m0, s98, 0x1e000
	s_setprio 1
	global_load_lds_dwordx4 v130, s[24:25]
	s_waitcnt vmcnt(6)
	s_barrier
	v_mfma_f32_16x16x32_bf16 v[30:33], v[216:219], v[182:185], v[30:33]
	v_mfma_f32_16x16x32_bf16 v[26:29], v[224:227], v[182:185], v[26:29]
	v_mfma_f32_16x16x32_bf16 v[22:25], v[216:219], v[190:193], v[22:25]
	v_mfma_f32_16x16x32_bf16 v[18:21], v[224:227], v[190:193], v[18:21]
	v_mfma_f32_16x16x32_bf16 v[14:17], v[216:219], v[200:203], v[14:17]
	v_mfma_f32_16x16x32_bf16 v[10:13], v[224:227], v[200:203], v[10:13]
	v_mfma_f32_16x16x32_bf16 v[6:9], v[216:219], v[208:211], v[6:9]
	v_mfma_f32_16x16x32_bf16 v[2:5], v[224:227], v[208:211], v[2:5]
	v_mfma_f32_16x16x32_bf16 v[30:33], v[220:223], v[186:189], v[30:33]
	v_mfma_f32_16x16x32_bf16 v[26:29], v[228:231], v[186:189], v[26:29]
	v_mfma_f32_16x16x32_bf16 v[22:25], v[220:223], v[196:199], v[22:25]
	v_mfma_f32_16x16x32_bf16 v[18:21], v[228:231], v[196:199], v[18:21]
	v_mfma_f32_16x16x32_bf16 v[14:17], v[220:223], v[204:207], v[14:17]
	v_mfma_f32_16x16x32_bf16 v[10:13], v[228:231], v[204:207], v[10:13]
	v_mfma_f32_16x16x32_bf16 v[6:9], v[220:223], v[212:215], v[6:9]
	v_mfma_f32_16x16x32_bf16 v[2:5], v[228:231], v[212:215], v[2:5]
	s_setprio 0
	s_add_i32 s18, s18, 2
	s_add_u32 s4, s4, 0x100
	s_addc_u32 s5, s5, 0
	s_cmp_lt_u32 s18, 28
	s_barrier
	s_cbranch_scc1 .LBB0_489
	ds_read_b128 v[152:155], v149
	ds_read_b128 v[156:159], v149 offset:1024
	ds_read_b128 v[160:163], v149 offset:2048
	ds_read_b128 v[164:167], v149 offset:3072
	ds_read_b128 v[168:171], v141
	ds_read_b128 v[172:175], v141 offset:1024
	ds_read_b128 v[176:179], v139
	ds_read_b128 v[180:183], v139 offset:1024
	ds_read_b128 v[184:187], v137
	ds_read_b128 v[188:191], v137 offset:1024
	ds_read_b128 v[196:199], v135
	ds_read_b128 v[200:203], v135 offset:1024
	s_add_u32 s4, s12, 0x80f80
	s_addc_u32 s5, s13, 0
	v_lshl_add_u64 v[132:133], s[4:5], 0, v[132:133]
	v_readfirstlane_b32 s12, v148
	s_mov_b32 m0, s12
	global_load_lds_dwordx4 v[132:133], off
	v_lshl_add_u64 v[130:131], s[4:5], 0, v[130:131]
	v_readfirstlane_b32 s4, v150
	s_mov_b32 m0, s4
	global_load_lds_dwordx4 v[130:131], off
	s_setprio 1
	s_barrier
	s_waitcnt lgkmcnt(0)
	v_mfma_f32_16x16x32_bf16 v[126:129], v[152:155], v[168:171], v[126:129]
	v_mfma_f32_16x16x32_bf16 v[122:125], v[160:163], v[168:171], v[122:125]
	v_mfma_f32_16x16x32_bf16 v[118:121], v[152:155], v[176:179], v[118:121]
	v_mfma_f32_16x16x32_bf16 v[114:117], v[160:163], v[176:179], v[114:117]
	v_mfma_f32_16x16x32_bf16 v[102:105], v[152:155], v[196:199], v[102:105]
	v_mfma_f32_16x16x32_bf16 v[98:101], v[160:163], v[196:199], v[98:101]
	v_mfma_f32_16x16x32_bf16 v[126:129], v[156:159], v[172:175], v[126:129]
	v_mfma_f32_16x16x32_bf16 v[122:125], v[164:167], v[172:175], v[122:125]
	v_mfma_f32_16x16x32_bf16 v[118:121], v[156:159], v[180:183], v[118:121]
	v_mfma_f32_16x16x32_bf16 v[114:117], v[164:167], v[180:183], v[114:117]
	v_mfma_f32_16x16x32_bf16 v[110:113], v[152:155], v[184:187], v[110:113]
	v_mfma_f32_16x16x32_bf16 v[106:109], v[160:163], v[184:187], v[106:109]
	v_mfma_f32_16x16x32_bf16 v[102:105], v[156:159], v[200:203], v[102:105]
	v_mfma_f32_16x16x32_bf16 v[98:101], v[164:167], v[200:203], v[98:101]
	v_mfma_f32_16x16x32_bf16 v[130:133], v[156:159], v[188:191], v[110:113]
	v_mfma_f32_16x16x32_bf16 v[148:151], v[164:167], v[188:191], v[106:109]
	s_barrier
	s_setprio 0
	s_nop 0
	ds_read_b128 v[106:109], v147
	ds_read_b128 v[110:113], v147 offset:1024
	ds_read_b128 v[204:207], v147 offset:2048
	ds_read_b128 v[208:211], v147 offset:3072
	s_setprio 1
	s_barrier
	s_waitcnt lgkmcnt(0)
	v_mfma_f32_16x16x32_bf16 v[86:89], v[106:109], v[176:179], v[86:89]
	v_mfma_f32_16x16x32_bf16 v[82:85], v[204:207], v[176:179], v[82:85]
	v_mfma_f32_16x16x32_bf16 v[70:73], v[106:109], v[196:199], v[70:73]
	v_mfma_f32_16x16x32_bf16 v[66:69], v[204:207], v[196:199], v[66:69]
	v_mfma_f32_16x16x32_bf16 v[94:97], v[106:109], v[168:171], v[94:97]
	v_mfma_f32_16x16x32_bf16 v[90:93], v[204:207], v[168:171], v[90:93]
	v_mfma_f32_16x16x32_bf16 v[86:89], v[110:113], v[180:183], v[86:89]
	v_mfma_f32_16x16x32_bf16 v[82:85], v[208:211], v[180:183], v[82:85]
	v_mfma_f32_16x16x32_bf16 v[78:81], v[106:109], v[184:187], v[78:81]
	v_mfma_f32_16x16x32_bf16 v[74:77], v[204:207], v[184:187], v[74:77]
	v_mfma_f32_16x16x32_bf16 v[70:73], v[110:113], v[200:203], v[70:73]
	v_mfma_f32_16x16x32_bf16 v[66:69], v[208:211], v[200:203], v[66:69]
	v_mfma_f32_16x16x32_bf16 v[212:215], v[110:113], v[172:175], v[94:97]
	v_mfma_f32_16x16x32_bf16 v[168:171], v[208:211], v[172:175], v[90:93]
	v_mfma_f32_16x16x32_bf16 v[172:175], v[110:113], v[188:191], v[78:81]
	v_mfma_f32_16x16x32_bf16 v[176:179], v[208:211], v[188:191], v[74:77]
	s_barrier
;   #define LDA(dst,b,h) for(int m=0;m<4;++m)for(int k=0;k<2;++k) \
;     dst[m][k]=*reinterpret_cast<const bf16x8*>((char*)SA(b,h)+lds_byte(wr*64+m*16+fr,k*32+fq*8))
;   #define LDB(dst,b,h) for(int n=0;n<2;++n)for(int k=0;k<2;++k) \
;     dst[n][k]=*reinterpret_cast<const bf16x8*>((char*)SB(b,h)+lds_byte(wc*32+n*16+fr,k*32+fq*8))
;   #define MMA(ai,bj,At,Bt_) do{__builtin_amdgcn_s_setprio(1); \
;     for(int m=0;m<4;++m)for(int n=0;n<2;++n)for(int k=0;k<2;++k) \
;       acc[ai][bj][m][n]=__builtin_amdgcn_mfma_f32_16x16x32_bf16(Bt_[n][k],At[m][k],acc[ai][bj][m][n],0,0,0); \
;     __builtin_amdgcn_s_setprio(0);}while(0)
;   #define WAIT_V(n) asm volatile("s_waitcnt vmcnt(" #n ")":::"memory")
;   #define WAIT_L(n) asm volatile("s_waitcnt lgkmcnt(" #n ")":::"memory")
;   #define BAR __builtin_amdgcn_s_barrier()
; template <bool TWO, class MID> ...
;     ...
;     LDA(At,0,1); WAIT_V(4); BAR; WAIT_L(0); MMA(1,0,At,B0); MMA(1,1,At,B1); BAR; }
;   { LDB(B0,1,0); LDA(At,1,0); WAIT_V(2); BAR; WAIT_L(0); MMA(0,0,At,B0); BAR;
;     LDB(B1,1,1); WAIT_V(0); BAR; WAIT_L(0); MMA(0,1,At,B1); BAR;
	s_setprio 0
	s_nop 0
	ds_read_b128 v[74:77], v141 offset:16384
	ds_read_b128 v[78:81], v141 offset:17408
	ds_read_b128 v[90:93], v139 offset:16384
	ds_read_b128 v[94:97], v139 offset:17408
	ds_read_b128 v[180:183], v137 offset:16384
	ds_read_b128 v[184:187], v137 offset:17408
	ds_read_b128 v[188:191], v135 offset:16384
	ds_read_b128 v[196:199], v135 offset:17408
	s_waitcnt vmcnt(4)
	s_setprio 1
	s_barrier
	s_waitcnt lgkmcnt(0)
	v_mfma_f32_16x16x32_bf16 v[62:65], v[152:155], v[74:77], v[62:65]
	v_mfma_f32_16x16x32_bf16 v[58:61], v[160:163], v[74:77], v[58:61]
	v_mfma_f32_16x16x32_bf16 v[54:57], v[152:155], v[90:93], v[54:57]
	v_mfma_f32_16x16x32_bf16 v[50:53], v[160:163], v[90:93], v[50:53]
	v_mfma_f32_16x16x32_bf16 v[38:41], v[152:155], v[188:191], v[38:41]
	v_mfma_f32_16x16x32_bf16 v[34:37], v[160:163], v[188:191], v[34:37]
	v_mfma_f32_16x16x32_bf16 v[62:65], v[156:159], v[78:81], v[62:65]
	v_mfma_f32_16x16x32_bf16 v[58:61], v[164:167], v[78:81], v[58:61]
	v_mfma_f32_16x16x32_bf16 v[54:57], v[156:159], v[94:97], v[54:57]
	v_mfma_f32_16x16x32_bf16 v[50:53], v[164:167], v[94:97], v[50:53]
	v_mfma_f32_16x16x32_bf16 v[46:49], v[152:155], v[180:183], v[46:49]
	v_mfma_f32_16x16x32_bf16 v[42:45], v[160:163], v[180:183], v[42:45]
	v_mfma_f32_16x16x32_bf16 v[38:41], v[156:159], v[196:199], v[38:41]
	v_mfma_f32_16x16x32_bf16 v[34:37], v[164:167], v[196:199], v[34:37]
	v_mfma_f32_16x16x32_bf16 v[200:203], v[156:159], v[184:187], v[46:49]
	v_mfma_f32_16x16x32_bf16 v[216:219], v[164:167], v[184:187], v[42:45]
	s_setprio 0
	s_setprio 1
	v_mfma_f32_16x16x32_bf16 v[22:25], v[106:109], v[90:93], v[22:25]
	v_mfma_f32_16x16x32_bf16 v[18:21], v[204:207], v[90:93], v[18:21]
	v_mfma_f32_16x16x32_bf16 v[6:9], v[106:109], v[188:191], v[6:9]
	v_mfma_f32_16x16x32_bf16 v[2:5], v[204:207], v[188:191], v[2:5]
	v_mfma_f32_16x16x32_bf16 v[30:33], v[106:109], v[74:77], v[30:33]
	v_mfma_f32_16x16x32_bf16 v[26:29], v[204:207], v[74:77], v[26:29]
	v_mfma_f32_16x16x32_bf16 v[22:25], v[110:113], v[94:97], v[22:25]
	v_mfma_f32_16x16x32_bf16 v[18:21], v[208:211], v[94:97], v[18:21]
	v_mfma_f32_16x16x32_bf16 v[14:17], v[106:109], v[180:183], v[14:17]
	v_mfma_f32_16x16x32_bf16 v[10:13], v[204:207], v[180:183], v[10:13]
	v_mfma_f32_16x16x32_bf16 v[6:9], v[110:113], v[196:199], v[6:9]
	v_mfma_f32_16x16x32_bf16 v[2:5], v[208:211], v[196:199], v[2:5]
	v_mfma_f32_16x16x32_bf16 v[152:155], v[110:113], v[78:81], v[30:33]
	v_mfma_f32_16x16x32_bf16 v[156:159], v[208:211], v[78:81], v[26:29]
	v_mfma_f32_16x16x32_bf16 v[160:163], v[110:113], v[184:187], v[14:17]
	v_mfma_f32_16x16x32_bf16 v[164:167], v[208:211], v[184:187], v[10:13]
	s_barrier
	s_setprio 0
	s_nop 0
	ds_read_b128 v[10:13], v145
	ds_read_b128 v[14:17], v145 offset:1024
	ds_read_b128 v[180:183], v145 offset:2048
	ds_read_b128 v[144:147], v145 offset:3072
	ds_read_b128 v[26:29], v141 offset:32768
	ds_read_b128 v[30:33], v141 offset:33792
	ds_read_b128 v[42:45], v139 offset:32768
	ds_read_b128 v[46:49], v139 offset:33792
	ds_read_b128 v[184:187], v137 offset:32768
	ds_read_b128 v[188:191], v137 offset:33792
	ds_read_b128 v[196:199], v135 offset:32768
	ds_read_b128 v[204:207], v135 offset:33792
	s_waitcnt vmcnt(2)
	s_setprio 1
	s_barrier
	s_waitcnt lgkmcnt(0)
	v_mfma_f32_16x16x32_bf16 v[74:77], v[10:13], v[26:29], v[126:129]
	v_mfma_f32_16x16x32_bf16 v[126:129], v[14:17], v[30:33], v[74:77]
	v_mfma_f32_16x16x32_bf16 v[74:77], v[180:183], v[26:29], v[122:125]
	v_mfma_f32_16x16x32_bf16 v[122:125], v[144:147], v[30:33], v[74:77]
	v_mfma_f32_16x16x32_bf16 v[74:77], v[10:13], v[42:45], v[118:121]
	v_mfma_f32_16x16x32_bf16 v[110:113], v[14:17], v[46:49], v[74:77]
	v_mfma_f32_16x16x32_bf16 v[74:77], v[180:183], v[42:45], v[114:117]
	v_mfma_f32_16x16x32_bf16 v[106:109], v[144:147], v[46:49], v[74:77]
	v_mfma_f32_16x16x32_bf16 v[74:77], v[10:13], v[184:187], v[130:133]
	v_mfma_f32_16x16x32_bf16 v[94:97], v[14:17], v[188:191], v[74:77]
	v_mfma_f32_16x16x32_bf16 v[74:77], v[180:183], v[184:187], v[148:151]
	v_mfma_f32_16x16x32_bf16 v[90:93], v[144:147], v[188:191], v[74:77]
	v_mfma_f32_16x16x32_bf16 v[74:77], v[10:13], v[196:199], v[102:105]
	v_mfma_f32_16x16x32_bf16 v[78:81], v[14:17], v[204:207], v[74:77]
	v_mfma_f32_16x16x32_bf16 v[74:77], v[180:183], v[196:199], v[98:101]
	v_mfma_f32_16x16x32_bf16 v[74:77], v[144:147], v[204:207], v[74:77]
	s_barrier
;   #define LDA(dst,b,h) for(int m=0;m<4;++m)for(int k=0;k<2;++k) \
;     dst[m][k]=*reinterpret_cast<const bf16x8*>((char*)SA(b,h)+lds_byte(wr*64+m*16+fr,k*32+fq*8))
;   #define LDB(dst,b,h) for(int n=0;n<2;++n)for(int k=0;k<2;++k) \
;     dst[n][k]=*reinterpret_cast<const bf16x8*>((char*)SB(b,h)+lds_byte(wc*32+n*16+fr,k*32+fq*8))
;   #define MMA(ai,bj,At,Bt_) do{__builtin_amdgcn_s_setprio(1); \
;     for(int m=0;m<4;++m)for(int n=0;n<2;++n)for(int k=0;k<2;++k) \
;       acc[ai][bj][m][n]=__builtin_amdgcn_mfma_f32_16x16x32_bf16(Bt_[n][k],At[m][k],acc[ai][bj][m][n],0,0,0); \
;     __builtin_amdgcn_s_setprio(0);}while(0)
;   #define WAIT_V(n) asm volatile("s_waitcnt vmcnt(" #n ")":::"memory")
;   #define WAIT_L(n) asm volatile("s_waitcnt lgkmcnt(" #n ")":::"memory")
;   #define BAR __builtin_amdgcn_s_barrier()
; template <bool TWO, class MID> ...
;     ...
;   { LDB(B0,1,0); LDA(At,1,0); WAIT_V(2); BAR; WAIT_L(0); MMA(0,0,At,B0); BAR;
;     LDB(B1,1,1); WAIT_V(0); BAR; WAIT_L(0); MMA(0,1,At,B1); BAR;
;     LDA(At,1,1); BAR; WAIT_L(0); MMA(1,0,At,B0); MMA(1,1,At,B1); BAR; }
;   if(wr==0)BAR;
	s_setprio 0
	ds_read_b128 v[130:133], v143
	ds_read_b128 v[148:151], v143 offset:1024
	ds_read_b128 v[208:211], v143 offset:2048
	ds_read_b128 v[220:223], v143 offset:3072
	s_waitcnt vmcnt(0)
	s_setprio 1
	s_barrier
	s_waitcnt lgkmcnt(0)
	v_mfma_f32_16x16x32_bf16 v[98:101], v[130:133], v[26:29], v[212:215]
	v_mfma_f32_16x16x32_bf16 v[26:29], v[208:211], v[26:29], v[168:171]
	v_mfma_f32_16x16x32_bf16 v[114:117], v[220:223], v[30:33], v[26:29]
	v_mfma_f32_16x16x32_bf16 v[26:29], v[130:133], v[42:45], v[86:89]
	v_mfma_f32_16x16x32_bf16 v[102:105], v[148:151], v[46:49], v[26:29]
	v_mfma_f32_16x16x32_bf16 v[26:29], v[208:211], v[42:45], v[82:85]
	v_mfma_f32_16x16x32_bf16 v[118:121], v[148:151], v[30:33], v[98:101]
	v_mfma_f32_16x16x32_bf16 v[98:101], v[220:223], v[46:49], v[26:29]
	v_mfma_f32_16x16x32_bf16 v[26:29], v[130:133], v[184:187], v[172:175]
	v_mfma_f32_16x16x32_bf16 v[86:89], v[148:151], v[188:191], v[26:29]
	v_mfma_f32_16x16x32_bf16 v[26:29], v[208:211], v[184:187], v[176:179]
	v_mfma_f32_16x16x32_bf16 v[82:85], v[220:223], v[188:191], v[26:29]
	v_mfma_f32_16x16x32_bf16 v[26:29], v[130:133], v[196:199], v[70:73]
	v_mfma_f32_16x16x32_bf16 v[70:73], v[148:151], v[204:207], v[26:29]
	v_mfma_f32_16x16x32_bf16 v[26:29], v[208:211], v[196:199], v[66:69]
	v_mfma_f32_16x16x32_bf16 v[66:69], v[220:223], v[204:207], v[26:29]
	s_barrier
	s_setprio 0
	ds_read_b128 v[168:171], v141 offset:49152
	ds_read_b128 v[140:143], v141 offset:50176
	ds_read_b128 v[172:175], v139 offset:49152
	ds_read_b128 v[176:179], v139 offset:50176
	ds_read_b128 v[184:187], v137 offset:49152
	ds_read_b128 v[136:139], v137 offset:50176
	ds_read_b128 v[188:191], v135 offset:49152
	ds_read_b128 v[196:199], v135 offset:50176
	s_setprio 1
	s_barrier
	s_waitcnt lgkmcnt(0)
	v_mfma_f32_16x16x32_bf16 v[26:29], v[10:13], v[168:171], v[62:65]
	v_mfma_f32_16x16x32_bf16 v[62:65], v[14:17], v[140:143], v[26:29]
	v_mfma_f32_16x16x32_bf16 v[26:29], v[180:183], v[168:171], v[58:61]
	v_mfma_f32_16x16x32_bf16 v[58:61], v[144:147], v[140:143], v[26:29]
	v_mfma_f32_16x16x32_bf16 v[26:29], v[10:13], v[172:175], v[54:57]
	v_mfma_f32_16x16x32_bf16 v[46:49], v[14:17], v[176:179], v[26:29]
	v_mfma_f32_16x16x32_bf16 v[26:29], v[180:183], v[172:175], v[50:53]
	v_mfma_f32_16x16x32_bf16 v[42:45], v[144:147], v[176:179], v[26:29]
	v_mfma_f32_16x16x32_bf16 v[26:29], v[10:13], v[184:187], v[200:203]
	v_mfma_f32_16x16x32_bf16 v[10:13], v[10:13], v[188:191], v[38:41]
	v_mfma_f32_16x16x32_bf16 v[30:33], v[14:17], v[136:139], v[26:29]
	v_mfma_f32_16x16x32_bf16 v[26:29], v[180:183], v[184:187], v[216:219]
	v_mfma_f32_16x16x32_bf16 v[14:17], v[14:17], v[196:199], v[10:13]
	v_mfma_f32_16x16x32_bf16 v[10:13], v[180:183], v[188:191], v[34:37]
	v_mfma_f32_16x16x32_bf16 v[26:29], v[144:147], v[136:139], v[26:29]
	v_mfma_f32_16x16x32_bf16 v[10:13], v[144:147], v[196:199], v[10:13]
	s_setprio 0
	s_setprio 1
	v_mfma_f32_16x16x32_bf16 v[34:37], v[130:133], v[168:171], v[152:155]
	v_mfma_f32_16x16x32_bf16 v[54:57], v[148:151], v[140:143], v[34:37]
	v_mfma_f32_16x16x32_bf16 v[34:37], v[208:211], v[168:171], v[156:159]
	v_mfma_f32_16x16x32_bf16 v[18:21], v[208:211], v[172:175], v[18:21]
	v_mfma_f32_16x16x32_bf16 v[50:53], v[220:223], v[140:143], v[34:37]
	v_mfma_f32_16x16x32_bf16 v[22:25], v[130:133], v[172:175], v[22:25]
	v_mfma_f32_16x16x32_bf16 v[34:37], v[220:223], v[176:179], v[18:21]
	v_mfma_f32_16x16x32_bf16 v[18:21], v[130:133], v[184:187], v[160:163]
	v_mfma_f32_16x16x32_bf16 v[38:41], v[148:151], v[176:179], v[22:25]
	v_mfma_f32_16x16x32_bf16 v[22:25], v[148:151], v[136:139], v[18:21]
	v_mfma_f32_16x16x32_bf16 v[18:21], v[208:211], v[184:187], v[164:167]
	v_mfma_f32_16x16x32_bf16 v[6:9], v[130:133], v[188:191], v[6:9]
	v_mfma_f32_16x16x32_bf16 v[2:5], v[208:211], v[188:191], v[2:5]
	v_mfma_f32_16x16x32_bf16 v[18:21], v[220:223], v[136:139], v[18:21]
	v_mfma_f32_16x16x32_bf16 v[6:9], v[148:151], v[196:199], v[6:9]
	v_mfma_f32_16x16x32_bf16 v[2:5], v[220:223], v[196:199], v[2:5]
	s_setprio 0
	v_cmp_gt_u32_e32 vcc, s30, v1
	s_barrier
	s_and_saveexec_b64 s[4:5], vcc
	s_cbranch_execz .LBB0_492
	s_barrier

;   #define LDA(dst,b,h) for(int m=0;m<4;++m)for(int k=0;k<2;++k) \
;     dst[m][k]=*reinterpret_cast<const bf16x8*>((char*)SA(b,h)+lds_byte(wr*64+m*16+fr,k*32+fq*8))
;   #define LDB(dst,b,h) for(int n=0;n<2;++n)for(int k=0;k<2;++k) \
;     dst[n][k]=*reinterpret_cast<const bf16x8*>((char*)SB(b,h)+lds_byte(wc*32+n*16+fr,k*32+fq*8))
;   #define MMA(ai,bj,At,Bt_) do{__builtin_amdgcn_s_setprio(1); \
;     for(int m=0;m<4;++m)for(int n=0;n<2;++n)for(int k=0;k<2;++k) \
;       acc[ai][bj][m][n]=__builtin_amdgcn_mfma_f32_16x16x32_bf16(Bt_[n][k],At[m][k],acc[ai][bj][m][n],0,0,0); \
;     __builtin_amdgcn_s_setprio(0);}while(0)
;   #define WAIT_V(n) asm volatile("s_waitcnt vmcnt(" #n ")":::"memory")
;   #define WAIT_L(n) asm volatile("s_waitcnt lgkmcnt(" #n ")":::"memory")
;   #define BAR __builtin_amdgcn_s_barrier()
;   #define SCHED __builtin_amdgcn_sched_barrier(0)
; template <bool TWO, class MID> ...
;     ...
;     LDB(B0,0,0); SCHED; LDA(At,0,0); STAGE_A(SA(1,1),1,t+1);
;     WAIT_L(8); BAR; WAIT_L(0); MMA(0,0,At,B0); BAR; SCHED;
;     LDB(B1,0,1); STAGE_B(SB(0,0),0,t+2);
;     BAR; WAIT_L(0); MMA(0,1,At,B1); BAR;
;     LDA(At,0,1); STAGE_A(SA(0,0),0,t+2);
;     BAR; WAIT_L(0); MMA(1,0,At,B0); BAR; SCHED;
;     STAGE_B(SB(0,1),1,t+2);
;     WAIT_V(6); BAR; MMA(1,1,At,B1); BAR;
.LBB0_562:
	ds_read_b128 v[166:169], v149
	ds_read_b128 v[170:173], v149 offset:1024
	ds_read_b128 v[174:177], v149 offset:2048
	ds_read_b128 v[178:181], v149 offset:3072
	ds_read_b128 v[182:185], v141
	ds_read_b128 v[186:189], v141 offset:1024
	ds_read_b128 v[190:193], v139
	ds_read_b128 v[196:199], v139 offset:1024
	ds_read_b128 v[200:203], v137
	ds_read_b128 v[204:207], v137 offset:1024
	ds_read_b128 v[208:211], v135
	ds_read_b128 v[212:215], v135 offset:1024
	s_add_u32 s23, s4, s12
	s_addc_u32 s24, s5, s13
	s_add_u32 m0, s98, 0xc000
	s_add_u32 s26, s23, 0x8080080
	s_addc_u32 s27, s24, 0
	global_load_lds_dwordx4 v132, s[26:27]
	s_add_u32 m0, s98, 0xe000
	s_setprio 1
	global_load_lds_dwordx4 v130, s[26:27]
	s_waitcnt lgkmcnt(8)
	s_barrier
	s_waitcnt lgkmcnt(0)
	v_mfma_f32_16x16x32_bf16 v[126:129], v[166:169], v[182:185], v[126:129]
	v_mfma_f32_16x16x32_bf16 v[122:125], v[174:177], v[182:185], v[122:125]
	v_mfma_f32_16x16x32_bf16 v[118:121], v[166:169], v[190:193], v[118:121]
	v_mfma_f32_16x16x32_bf16 v[114:117], v[174:177], v[190:193], v[114:117]
	v_mfma_f32_16x16x32_bf16 v[110:113], v[166:169], v[200:203], v[110:113]
	v_mfma_f32_16x16x32_bf16 v[106:109], v[174:177], v[200:203], v[106:109]
	v_mfma_f32_16x16x32_bf16 v[102:105], v[166:169], v[208:211], v[102:105]
	v_mfma_f32_16x16x32_bf16 v[98:101], v[174:177], v[208:211], v[98:101]
	v_mfma_f32_16x16x32_bf16 v[126:129], v[170:173], v[186:189], v[126:129]
	v_mfma_f32_16x16x32_bf16 v[122:125], v[178:181], v[186:189], v[122:125]
	v_mfma_f32_16x16x32_bf16 v[118:121], v[170:173], v[196:199], v[118:121]
	v_mfma_f32_16x16x32_bf16 v[114:117], v[178:181], v[196:199], v[114:117]
	v_mfma_f32_16x16x32_bf16 v[110:113], v[170:173], v[204:207], v[110:113]
	v_mfma_f32_16x16x32_bf16 v[106:109], v[178:181], v[204:207], v[106:109]
	v_mfma_f32_16x16x32_bf16 v[102:105], v[170:173], v[212:215], v[102:105]
	v_mfma_f32_16x16x32_bf16 v[98:101], v[178:181], v[212:215], v[98:101]
	s_barrier
	s_setprio 0
	s_add_u32 s25, s4, s14
	ds_read_b128 v[216:219], v147
	ds_read_b128 v[220:223], v147 offset:1024
	ds_read_b128 v[224:227], v147 offset:2048
	ds_read_b128 v[228:231], v147 offset:3072
	s_addc_u32 s26, s5, s15
	s_add_u32 m0, s98, 0x10000
	s_add_u32 s28, s25, 0x3c00100
	s_addc_u32 s29, s26, 0
	global_load_lds_dwordx4 v132, s[28:29]
	s_add_u32 m0, s98, 0x12000
	s_setprio 1
	global_load_lds_dwordx4 v130, s[28:29]
	s_barrier
	s_waitcnt lgkmcnt(0)
	v_mfma_f32_16x16x32_bf16 v[94:97], v[216:219], v[182:185], v[94:97]
	v_mfma_f32_16x16x32_bf16 v[90:93], v[224:227], v[182:185], v[90:93]
	v_mfma_f32_16x16x32_bf16 v[86:89], v[216:219], v[190:193], v[86:89]
	v_mfma_f32_16x16x32_bf16 v[82:85], v[224:227], v[190:193], v[82:85]
	v_mfma_f32_16x16x32_bf16 v[78:81], v[216:219], v[200:203], v[78:81]
	v_mfma_f32_16x16x32_bf16 v[74:77], v[224:227], v[200:203], v[74:77]
	v_mfma_f32_16x16x32_bf16 v[70:73], v[216:219], v[208:211], v[70:73]
	v_mfma_f32_16x16x32_bf16 v[66:69], v[224:227], v[208:211], v[66:69]
	v_mfma_f32_16x16x32_bf16 v[94:97], v[220:223], v[186:189], v[94:97]
	v_mfma_f32_16x16x32_bf16 v[90:93], v[228:231], v[186:189], v[90:93]
	v_mfma_f32_16x16x32_bf16 v[86:89], v[220:223], v[196:199], v[86:89]
	v_mfma_f32_16x16x32_bf16 v[82:85], v[228:231], v[196:199], v[82:85]
	v_mfma_f32_16x16x32_bf16 v[78:81], v[220:223], v[204:207], v[78:81]
	v_mfma_f32_16x16x32_bf16 v[74:77], v[228:231], v[204:207], v[74:77]
	v_mfma_f32_16x16x32_bf16 v[70:73], v[220:223], v[212:215], v[70:73]
	v_mfma_f32_16x16x32_bf16 v[66:69], v[228:231], v[212:215], v[66:69]
	s_barrier
	s_setprio 0
	ds_read_b128 v[182:185], v141 offset:16384
	ds_read_b128 v[186:189], v141 offset:17408
	ds_read_b128 v[190:193], v139 offset:16384
	ds_read_b128 v[196:199], v139 offset:17408
	ds_read_b128 v[200:203], v137 offset:16384
	ds_read_b128 v[204:207], v137 offset:17408
	ds_read_b128 v[208:211], v135 offset:16384
	ds_read_b128 v[212:215], v135 offset:17408
	s_add_u32 m0, s98, 0x0
	s_add_u32 s28, s23, 0x8000100
	s_addc_u32 s29, s24, 0
	global_load_lds_dwordx4 v132, s[28:29]
	s_add_u32 m0, s98, 0x2000
	s_setprio 1
	global_load_lds_dwordx4 v130, s[28:29]
	s_barrier
	s_waitcnt lgkmcnt(0)
	v_mfma_f32_16x16x32_bf16 v[62:65], v[166:169], v[182:185], v[62:65]
	v_mfma_f32_16x16x32_bf16 v[58:61], v[174:177], v[182:185], v[58:61]
	v_mfma_f32_16x16x32_bf16 v[54:57], v[166:169], v[190:193], v[54:57]
	v_mfma_f32_16x16x32_bf16 v[50:53], v[174:177], v[190:193], v[50:53]
	v_mfma_f32_16x16x32_bf16 v[46:49], v[166:169], v[200:203], v[46:49]
	v_mfma_f32_16x16x32_bf16 v[42:45], v[174:177], v[200:203], v[42:45]
	v_mfma_f32_16x16x32_bf16 v[38:41], v[166:169], v[208:211], v[38:41]
	v_mfma_f32_16x16x32_bf16 v[34:37], v[174:177], v[208:211], v[34:37]
	v_mfma_f32_16x16x32_bf16 v[62:65], v[170:173], v[186:189], v[62:65]
	v_mfma_f32_16x16x32_bf16 v[58:61], v[178:181], v[186:189], v[58:61]
	v_mfma_f32_16x16x32_bf16 v[54:57], v[170:173], v[196:199], v[54:57]
	v_mfma_f32_16x16x32_bf16 v[50:53], v[178:181], v[196:199], v[50:53]
	v_mfma_f32_16x16x32_bf16 v[46:49], v[170:173], v[204:207], v[46:49]
	v_mfma_f32_16x16x32_bf16 v[42:45], v[178:181], v[204:207], v[42:45]
	v_mfma_f32_16x16x32_bf16 v[38:41], v[170:173], v[212:215], v[38:41]
	v_mfma_f32_16x16x32_bf16 v[34:37], v[178:181], v[212:215], v[34:37]
	s_barrier
	s_setprio 0
	s_add_u32 m0, s98, 0x14000
	s_add_u32 s28, s25, 0x3c80100
	s_addc_u32 s29, s26, 0
	global_load_lds_dwordx4 v132, s[28:29]
	s_add_u32 m0, s98, 0x16000
	s_setprio 1
	global_load_lds_dwordx4 v130, s[28:29]
	s_waitcnt vmcnt(6)
	s_barrier
;   #define LDA(dst,b,h) for(int m=0;m<4;++m)for(int k=0;k<2;++k) \
;     dst[m][k]=*reinterpret_cast<const bf16x8*>((char*)SA(b,h)+lds_byte(wr*64+m*16+fr,k*32+fq*8))
;   #define LDB(dst,b,h) for(int n=0;n<2;++n)for(int k=0;k<2;++k) \
;     dst[n][k]=*reinterpret_cast<const bf16x8*>((char*)SB(b,h)+lds_byte(wc*32+n*16+fr,k*32+fq*8))
;   #define MMA(ai,bj,At,Bt_) do{__builtin_amdgcn_s_setprio(1); \
;     for(int m=0;m<4;++m)for(int n=0;n<2;++n)for(int k=0;k<2;++k) \
;       acc[ai][bj][m][n]=__builtin_amdgcn_mfma_f32_16x16x32_bf16(Bt_[n][k],At[m][k],acc[ai][bj][m][n],0,0,0); \
;     __builtin_amdgcn_s_setprio(0);}while(0)
;   #define WAIT_V(n) asm volatile("s_waitcnt vmcnt(" #n ")":::"memory")
;   #define WAIT_L(n) asm volatile("s_waitcnt lgkmcnt(" #n ")":::"memory")
;   #define BAR __builtin_amdgcn_s_barrier()
;   #define SCHED __builtin_amdgcn_sched_barrier(0)
; template <bool TWO, class MID> ...
;     ...
;     WAIT_V(6); BAR; MMA(1,1,At,B1); BAR;
;     LDB(B0,1,0); SCHED; LDA(At,1,0); STAGE_A(SA(0,1),1,t+2);
;     WAIT_L(8); BAR; WAIT_L(0); MMA(0,0,At,B0); BAR; SCHED;
;     LDB(B1,1,1); STAGE_B(SB(1,0),0,t+3);
;     BAR; WAIT_L(0); MMA(0,1,At,B1); BAR;
;     LDA(At,1,1); STAGE_A(SA(1,0),0,t+3);
	v_mfma_f32_16x16x32_bf16 v[30:33], v[216:219], v[182:185], v[30:33]
	v_mfma_f32_16x16x32_bf16 v[26:29], v[224:227], v[182:185], v[26:29]
	v_mfma_f32_16x16x32_bf16 v[22:25], v[216:219], v[190:193], v[22:25]
	v_mfma_f32_16x16x32_bf16 v[18:21], v[224:227], v[190:193], v[18:21]
	v_mfma_f32_16x16x32_bf16 v[14:17], v[216:219], v[200:203], v[14:17]
	v_mfma_f32_16x16x32_bf16 v[10:13], v[224:227], v[200:203], v[10:13]
	v_mfma_f32_16x16x32_bf16 v[6:9], v[216:219], v[208:211], v[6:9]
	v_mfma_f32_16x16x32_bf16 v[2:5], v[224:227], v[208:211], v[2:5]
	v_mfma_f32_16x16x32_bf16 v[30:33], v[220:223], v[186:189], v[30:33]
	v_mfma_f32_16x16x32_bf16 v[26:29], v[228:231], v[186:189], v[26:29]
	v_mfma_f32_16x16x32_bf16 v[22:25], v[220:223], v[196:199], v[22:25]
	v_mfma_f32_16x16x32_bf16 v[18:21], v[228:231], v[196:199], v[18:21]
	v_mfma_f32_16x16x32_bf16 v[14:17], v[220:223], v[204:207], v[14:17]
	v_mfma_f32_16x16x32_bf16 v[10:13], v[228:231], v[204:207], v[10:13]
	v_mfma_f32_16x16x32_bf16 v[6:9], v[220:223], v[212:215], v[6:9]
	v_mfma_f32_16x16x32_bf16 v[2:5], v[228:231], v[212:215], v[2:5]
	s_barrier
	s_setprio 0
	ds_read_b128 v[166:169], v145
	ds_read_b128 v[170:173], v145 offset:1024
	ds_read_b128 v[174:177], v145 offset:2048
	ds_read_b128 v[178:181], v145 offset:3072
	ds_read_b128 v[182:185], v141 offset:32768
	ds_read_b128 v[186:189], v141 offset:33792
	ds_read_b128 v[190:193], v139 offset:32768
	ds_read_b128 v[196:199], v139 offset:33792
	ds_read_b128 v[200:203], v137 offset:32768
	ds_read_b128 v[204:207], v137 offset:33792
	ds_read_b128 v[208:211], v135 offset:32768
	ds_read_b128 v[212:215], v135 offset:33792
	s_add_u32 m0, s98, 0x4000
	s_add_u32 s28, s23, 0x8080100
	s_addc_u32 s29, s24, 0
	global_load_lds_dwordx4 v132, s[28:29]
	s_add_u32 m0, s98, 0x6000
	s_setprio 1
	global_load_lds_dwordx4 v130, s[28:29]
	s_waitcnt lgkmcnt(8)
	s_barrier
	s_waitcnt lgkmcnt(0)
	v_mfma_f32_16x16x32_bf16 v[126:129], v[166:169], v[182:185], v[126:129]
	v_mfma_f32_16x16x32_bf16 v[122:125], v[174:177], v[182:185], v[122:125]
	v_mfma_f32_16x16x32_bf16 v[118:121], v[166:169], v[190:193], v[118:121]
	v_mfma_f32_16x16x32_bf16 v[114:117], v[174:177], v[190:193], v[114:117]
	v_mfma_f32_16x16x32_bf16 v[110:113], v[166:169], v[200:203], v[110:113]
	v_mfma_f32_16x16x32_bf16 v[106:109], v[174:177], v[200:203], v[106:109]
	v_mfma_f32_16x16x32_bf16 v[102:105], v[166:169], v[208:211], v[102:105]
	v_mfma_f32_16x16x32_bf16 v[98:101], v[174:177], v[208:211], v[98:101]
	v_mfma_f32_16x16x32_bf16 v[126:129], v[170:173], v[186:189], v[126:129]
	v_mfma_f32_16x16x32_bf16 v[122:125], v[178:181], v[186:189], v[122:125]
	v_mfma_f32_16x16x32_bf16 v[118:121], v[170:173], v[196:199], v[118:121]
	v_mfma_f32_16x16x32_bf16 v[114:117], v[178:181], v[196:199], v[114:117]
	v_mfma_f32_16x16x32_bf16 v[110:113], v[170:173], v[204:207], v[110:113]
	v_mfma_f32_16x16x32_bf16 v[106:109], v[178:181], v[204:207], v[106:109]
	v_mfma_f32_16x16x32_bf16 v[102:105], v[170:173], v[212:215], v[102:105]
	v_mfma_f32_16x16x32_bf16 v[98:101], v[178:181], v[212:215], v[98:101]
	s_barrier
	s_setprio 0
	ds_read_b128 v[216:219], v143
	ds_read_b128 v[220:223], v143 offset:1024
	ds_read_b128 v[224:227], v143 offset:2048
	ds_read_b128 v[228:231], v143 offset:3072
	s_add_u32 m0, s98, 0x18000
	s_add_u32 s28, s25, 0x3c00180
	s_addc_u32 s29, s26, 0
	global_load_lds_dwordx4 v132, s[28:29]
	s_add_u32 m0, s98, 0x1a000
	s_setprio 1
	global_load_lds_dwordx4 v130, s[28:29]
	s_barrier
	s_waitcnt lgkmcnt(0)
	v_mfma_f32_16x16x32_bf16 v[94:97], v[216:219], v[182:185], v[94:97]
	v_mfma_f32_16x16x32_bf16 v[90:93], v[224:227], v[182:185], v[90:93]
	v_mfma_f32_16x16x32_bf16 v[86:89], v[216:219], v[190:193], v[86:89]
	v_mfma_f32_16x16x32_bf16 v[82:85], v[224:227], v[190:193], v[82:85]
	v_mfma_f32_16x16x32_bf16 v[78:81], v[216:219], v[200:203], v[78:81]
	v_mfma_f32_16x16x32_bf16 v[74:77], v[224:227], v[200:203], v[74:77]
	v_mfma_f32_16x16x32_bf16 v[70:73], v[216:219], v[208:211], v[70:73]
	v_mfma_f32_16x16x32_bf16 v[66:69], v[224:227], v[208:211], v[66:69]
	v_mfma_f32_16x16x32_bf16 v[94:97], v[220:223], v[186:189], v[94:97]
	v_mfma_f32_16x16x32_bf16 v[90:93], v[228:231], v[186:189], v[90:93]
	v_mfma_f32_16x16x32_bf16 v[86:89], v[220:223], v[196:199], v[86:89]
	v_mfma_f32_16x16x32_bf16 v[82:85], v[228:231], v[196:199], v[82:85]
	v_mfma_f32_16x16x32_bf16 v[78:81], v[220:223], v[204:207], v[78:81]
	v_mfma_f32_16x16x32_bf16 v[74:77], v[228:231], v[204:207], v[74:77]
	v_mfma_f32_16x16x32_bf16 v[70:73], v[220:223], v[212:215], v[70:73]
	v_mfma_f32_16x16x32_bf16 v[66:69], v[228:231], v[212:215], v[66:69]
	s_barrier
	s_setprio 0
	ds_read_b128 v[182:185], v141 offset:49152
	ds_read_b128 v[186:189], v141 offset:50176
	ds_read_b128 v[190:193], v139 offset:49152
	ds_read_b128 v[196:199], v139 offset:50176
	ds_read_b128 v[200:203], v137 offset:49152
	ds_read_b128 v[204:207], v137 offset:50176
	ds_read_b128 v[208:211], v135 offset:49152
	ds_read_b128 v[212:215], v135 offset:50176
	s_add_u32 m0, s98, 0x8000
	s_add_u32 s28, s23, 0x8000180
	s_addc_u32 s29, s24, 0
	global_load_lds_dwordx4 v132, s[28:29]
	s_add_u32 m0, s98, 0xa000
	s_setprio 1
	global_load_lds_dwordx4 v130, s[28:29]
	s_barrier
;   #define LDA(dst,b,h) for(int m=0;m<4;++m)for(int k=0;k<2;++k) \
;     dst[m][k]=*reinterpret_cast<const bf16x8*>((char*)SA(b,h)+lds_byte(wr*64+m*16+fr,k*32+fq*8))
;   #define LDB(dst,b,h) for(int n=0;n<2;++n)for(int k=0;k<2;++k) \
;     dst[n][k]=*reinterpret_cast<const bf16x8*>((char*)SB(b,h)+lds_byte(wc*32+n*16+fr,k*32+fq*8))
;   #define MMA(ai,bj,At,Bt_) do{__builtin_amdgcn_s_setprio(1); \
;     for(int m=0;m<4;++m)for(int n=0;n<2;++n)for(int k=0;k<2;++k) \
;       acc[ai][bj][m][n]=__builtin_amdgcn_mfma_f32_16x16x32_bf16(Bt_[n][k],At[m][k],acc[ai][bj][m][n],0,0,0); \
;     __builtin_amdgcn_s_setprio(0);}while(0)
;   #define WAIT_V(n) asm volatile("s_waitcnt vmcnt(" #n ")":::"memory")
;   #define WAIT_L(n) asm volatile("s_waitcnt lgkmcnt(" #n ")":::"memory")
;   #define BAR __builtin_amdgcn_s_barrier()
;   #define SCHED __builtin_amdgcn_sched_barrier(0)
; template <bool TWO, class MID> ...
;     ...
;     LDA(At,1,1); STAGE_A(SA(1,0),0,t+3);
;     BAR; WAIT_L(0); MMA(1,0,At,B0); BAR; SCHED;
;     STAGE_B(SB(1,1),1,t+3);
;     WAIT_V(6); BAR; MMA(1,1,At,B1); BAR;
;   }
;   { LDB(B0,0,0); LDA(At,0,0); STAGE_A(SA(1,1),1,nt-1);
;     BAR; WAIT_L(0); MMA(0,0,At,B0); BAR;
;     LDB(B1,0,1); BAR; WAIT_L(0); MMA(0,1,At,B1); BAR;
	s_waitcnt lgkmcnt(0)
	v_mfma_f32_16x16x32_bf16 v[62:65], v[166:169], v[182:185], v[62:65]
	v_mfma_f32_16x16x32_bf16 v[58:61], v[174:177], v[182:185], v[58:61]
	v_mfma_f32_16x16x32_bf16 v[54:57], v[166:169], v[190:193], v[54:57]
	v_mfma_f32_16x16x32_bf16 v[50:53], v[174:177], v[190:193], v[50:53]
	v_mfma_f32_16x16x32_bf16 v[46:49], v[166:169], v[200:203], v[46:49]
	v_mfma_f32_16x16x32_bf16 v[42:45], v[174:177], v[200:203], v[42:45]
	v_mfma_f32_16x16x32_bf16 v[38:41], v[166:169], v[208:211], v[38:41]
	v_mfma_f32_16x16x32_bf16 v[34:37], v[174:177], v[208:211], v[34:37]
	v_mfma_f32_16x16x32_bf16 v[62:65], v[170:173], v[186:189], v[62:65]
	v_mfma_f32_16x16x32_bf16 v[58:61], v[178:181], v[186:189], v[58:61]
	v_mfma_f32_16x16x32_bf16 v[54:57], v[170:173], v[196:199], v[54:57]
	v_mfma_f32_16x16x32_bf16 v[50:53], v[178:181], v[196:199], v[50:53]
	v_mfma_f32_16x16x32_bf16 v[46:49], v[170:173], v[204:207], v[46:49]
	v_mfma_f32_16x16x32_bf16 v[42:45], v[178:181], v[204:207], v[42:45]
	v_mfma_f32_16x16x32_bf16 v[38:41], v[170:173], v[212:215], v[38:41]
	v_mfma_f32_16x16x32_bf16 v[34:37], v[178:181], v[212:215], v[34:37]
	s_barrier
	s_setprio 0
	s_add_u32 m0, s98, 0x1c000
	s_add_u32 s24, s25, 0x3c80180
	s_addc_u32 s25, s26, 0
	global_load_lds_dwordx4 v132, s[24:25]
	s_add_u32 m0, s98, 0x1e000
	s_setprio 1
	global_load_lds_dwordx4 v130, s[24:25]
	s_waitcnt vmcnt(6)
	s_barrier
	v_mfma_f32_16x16x32_bf16 v[30:33], v[216:219], v[182:185], v[30:33]
	v_mfma_f32_16x16x32_bf16 v[26:29], v[224:227], v[182:185], v[26:29]
	v_mfma_f32_16x16x32_bf16 v[22:25], v[216:219], v[190:193], v[22:25]
	v_mfma_f32_16x16x32_bf16 v[18:21], v[224:227], v[190:193], v[18:21]
	v_mfma_f32_16x16x32_bf16 v[14:17], v[216:219], v[200:203], v[14:17]
	v_mfma_f32_16x16x32_bf16 v[10:13], v[224:227], v[200:203], v[10:13]
	v_mfma_f32_16x16x32_bf16 v[6:9], v[216:219], v[208:211], v[6:9]
	v_mfma_f32_16x16x32_bf16 v[2:5], v[224:227], v[208:211], v[2:5]
	v_mfma_f32_16x16x32_bf16 v[30:33], v[220:223], v[186:189], v[30:33]
	v_mfma_f32_16x16x32_bf16 v[26:29], v[228:231], v[186:189], v[26:29]
	v_mfma_f32_16x16x32_bf16 v[22:25], v[220:223], v[196:199], v[22:25]
	v_mfma_f32_16x16x32_bf16 v[18:21], v[228:231], v[196:199], v[18:21]
	v_mfma_f32_16x16x32_bf16 v[14:17], v[220:223], v[204:207], v[14:17]
	v_mfma_f32_16x16x32_bf16 v[10:13], v[228:231], v[204:207], v[10:13]
	v_mfma_f32_16x16x32_bf16 v[6:9], v[220:223], v[212:215], v[6:9]
	v_mfma_f32_16x16x32_bf16 v[2:5], v[228:231], v[212:215], v[2:5]
	s_setprio 0
	s_add_i32 s22, s22, 2
	s_add_u32 s4, s4, 0x100
	s_addc_u32 s5, s5, 0
	s_cmp_lt_u32 s22, 28
	s_barrier
	s_cbranch_scc1 .LBB0_562
	ds_read_b128 v[152:155], v149
	ds_read_b128 v[156:159], v149 offset:1024
	ds_read_b128 v[160:163], v149 offset:2048
	ds_read_b128 v[164:167], v149 offset:3072
	ds_read_b128 v[168:171], v141
	ds_read_b128 v[172:175], v141 offset:1024
	ds_read_b128 v[176:179], v139
	ds_read_b128 v[180:183], v139 offset:1024
	ds_read_b128 v[184:187], v137
	ds_read_b128 v[188:191], v137 offset:1024
	ds_read_b128 v[196:199], v135
	ds_read_b128 v[200:203], v135 offset:1024
	s_add_u32 s4, s19, 0x80f80
	s_addc_u32 s5, s21, 0
	v_lshl_add_u64 v[132:133], s[4:5], 0, v[132:133]
	v_readfirstlane_b32 s12, v148
	s_mov_b32 m0, s12
	global_load_lds_dwordx4 v[132:133], off
	v_lshl_add_u64 v[130:131], s[4:5], 0, v[130:131]
	v_readfirstlane_b32 s4, v150
	s_mov_b32 m0, s4
	global_load_lds_dwordx4 v[130:131], off
	s_setprio 1
	s_barrier
	s_waitcnt lgkmcnt(0)
	v_mfma_f32_16x16x32_bf16 v[126:129], v[152:155], v[168:171], v[126:129]
	v_mfma_f32_16x16x32_bf16 v[122:125], v[160:163], v[168:171], v[122:125]
	v_mfma_f32_16x16x32_bf16 v[114:117], v[160:163], v[176:179], v[114:117]
	v_mfma_f32_16x16x32_bf16 v[106:109], v[160:163], v[184:187], v[106:109]
	v_mfma_f32_16x16x32_bf16 v[98:101], v[160:163], v[196:199], v[98:101]
	v_mfma_f32_16x16x32_bf16 v[126:129], v[156:159], v[172:175], v[126:129]
	v_mfma_f32_16x16x32_bf16 v[122:125], v[164:167], v[172:175], v[122:125]
	v_mfma_f32_16x16x32_bf16 v[118:121], v[152:155], v[176:179], v[118:121]
	v_mfma_f32_16x16x32_bf16 v[114:117], v[164:167], v[180:183], v[114:117]
	v_mfma_f32_16x16x32_bf16 v[110:113], v[152:155], v[184:187], v[110:113]
	v_mfma_f32_16x16x32_bf16 v[106:109], v[164:167], v[188:191], v[106:109]
	v_mfma_f32_16x16x32_bf16 v[102:105], v[152:155], v[196:199], v[102:105]
	v_mfma_f32_16x16x32_bf16 v[98:101], v[164:167], v[200:203], v[98:101]
	v_mfma_f32_16x16x32_bf16 v[130:133], v[156:159], v[180:183], v[118:121]
	v_mfma_f32_16x16x32_bf16 v[148:151], v[156:159], v[188:191], v[110:113]
	v_mfma_f32_16x16x32_bf16 v[204:207], v[156:159], v[200:203], v[102:105]
	s_barrier
	s_setprio 0
	s_nop 0
	ds_read_b128 v[102:105], v147
	ds_read_b128 v[110:113], v147 offset:1024
	ds_read_b128 v[118:121], v147 offset:2048
	ds_read_b128 v[208:211], v147 offset:3072
	s_setprio 1
	s_barrier
	s_waitcnt lgkmcnt(0)
	v_mfma_f32_16x16x32_bf16 v[90:93], v[118:121], v[168:171], v[90:93]
	v_mfma_f32_16x16x32_bf16 v[82:85], v[118:121], v[176:179], v[82:85]
	v_mfma_f32_16x16x32_bf16 v[74:77], v[118:121], v[184:187], v[74:77]
	v_mfma_f32_16x16x32_bf16 v[66:69], v[118:121], v[196:199], v[66:69]
	v_mfma_f32_16x16x32_bf16 v[94:97], v[102:105], v[168:171], v[94:97]
	v_mfma_f32_16x16x32_bf16 v[90:93], v[208:211], v[172:175], v[90:93]
	v_mfma_f32_16x16x32_bf16 v[86:89], v[102:105], v[176:179], v[86:89]
	v_mfma_f32_16x16x32_bf16 v[82:85], v[208:211], v[180:183], v[82:85]
	v_mfma_f32_16x16x32_bf16 v[78:81], v[102:105], v[184:187], v[78:81]
	v_mfma_f32_16x16x32_bf16 v[74:77], v[208:211], v[188:191], v[74:77]
	v_mfma_f32_16x16x32_bf16 v[70:73], v[102:105], v[196:199], v[70:73]
	v_mfma_f32_16x16x32_bf16 v[66:69], v[208:211], v[200:203], v[66:69]
	v_mfma_f32_16x16x32_bf16 v[212:215], v[110:113], v[172:175], v[94:97]
	v_mfma_f32_16x16x32_bf16 v[168:171], v[110:113], v[180:183], v[86:89]
	v_mfma_f32_16x16x32_bf16 v[172:175], v[110:113], v[188:191], v[78:81]
	v_mfma_f32_16x16x32_bf16 v[176:179], v[110:113], v[200:203], v[70:73]
	s_barrier
;   #define LDA(dst,b,h) for(int m=0;m<4;++m)for(int k=0;k<2;++k) \
;     dst[m][k]=*reinterpret_cast<const bf16x8*>((char*)SA(b,h)+lds_byte(wr*64+m*16+fr,k*32+fq*8))
;   #define LDB(dst,b,h) for(int n=0;n<2;++n)for(int k=0;k<2;++k) \
;     dst[n][k]=*reinterpret_cast<const bf16x8*>((char*)SB(b,h)+lds_byte(wc*32+n*16+fr,k*32+fq*8))
;   #define MMA(ai,bj,At,Bt_) do{__builtin_amdgcn_s_setprio(1); \
;     for(int m=0;m<4;++m)for(int n=0;n<2;++n)for(int k=0;k<2;++k) \
;       acc[ai][bj][m][n]=__builtin_amdgcn_mfma_f32_16x16x32_bf16(Bt_[n][k],At[m][k],acc[ai][bj][m][n],0,0,0); \
;     __builtin_amdgcn_s_setprio(0);}while(0)
;   #define WAIT_V(n) asm volatile("s_waitcnt vmcnt(" #n ")":::"memory")
;   #define WAIT_L(n) asm volatile("s_waitcnt lgkmcnt(" #n ")":::"memory")
;   #define BAR __builtin_amdgcn_s_barrier()
; template <bool TWO, class MID> ...
;     ...
;     LDA(At,0,1); WAIT_V(4); BAR; WAIT_L(0); MMA(1,0,At,B0); MMA(1,1,At,B1); BAR; }
;   { LDB(B0,1,0); LDA(At,1,0); WAIT_V(2); BAR; WAIT_L(0); MMA(0,0,At,B0); BAR;
;     LDB(B1,1,1); WAIT_V(0); BAR; WAIT_L(0); MMA(0,1,At,B1); BAR;
	s_setprio 0
	s_nop 0
	ds_read_b128 v[70:73], v141 offset:16384
	ds_read_b128 v[78:81], v141 offset:17408
	ds_read_b128 v[86:89], v139 offset:16384
	ds_read_b128 v[94:97], v139 offset:17408
	ds_read_b128 v[180:183], v137 offset:16384
	ds_read_b128 v[184:187], v137 offset:17408
	ds_read_b128 v[188:191], v135 offset:16384
	ds_read_b128 v[196:199], v135 offset:17408
	s_waitcnt vmcnt(4)
	s_setprio 1
	s_barrier
	s_waitcnt lgkmcnt(0)
	v_mfma_f32_16x16x32_bf16 v[62:65], v[152:155], v[70:73], v[62:65]
	v_mfma_f32_16x16x32_bf16 v[58:61], v[160:163], v[70:73], v[58:61]
	v_mfma_f32_16x16x32_bf16 v[54:57], v[152:155], v[86:89], v[54:57]
	v_mfma_f32_16x16x32_bf16 v[50:53], v[160:163], v[86:89], v[50:53]
	v_mfma_f32_16x16x32_bf16 v[38:41], v[152:155], v[188:191], v[38:41]
	v_mfma_f32_16x16x32_bf16 v[34:37], v[160:163], v[188:191], v[34:37]
	v_mfma_f32_16x16x32_bf16 v[62:65], v[156:159], v[78:81], v[62:65]
	v_mfma_f32_16x16x32_bf16 v[58:61], v[164:167], v[78:81], v[58:61]
	v_mfma_f32_16x16x32_bf16 v[54:57], v[156:159], v[94:97], v[54:57]
	v_mfma_f32_16x16x32_bf16 v[50:53], v[164:167], v[94:97], v[50:53]
	v_mfma_f32_16x16x32_bf16 v[46:49], v[152:155], v[180:183], v[46:49]
	v_mfma_f32_16x16x32_bf16 v[42:45], v[160:163], v[180:183], v[42:45]
	v_mfma_f32_16x16x32_bf16 v[38:41], v[156:159], v[196:199], v[38:41]
	v_mfma_f32_16x16x32_bf16 v[34:37], v[164:167], v[196:199], v[34:37]
	v_mfma_f32_16x16x32_bf16 v[200:203], v[156:159], v[184:187], v[46:49]
	v_mfma_f32_16x16x32_bf16 v[216:219], v[164:167], v[184:187], v[42:45]
	s_setprio 0
	s_setprio 1
	v_mfma_f32_16x16x32_bf16 v[22:25], v[102:105], v[86:89], v[22:25]
	v_mfma_f32_16x16x32_bf16 v[18:21], v[118:121], v[86:89], v[18:21]
	v_mfma_f32_16x16x32_bf16 v[6:9], v[102:105], v[188:191], v[6:9]
	v_mfma_f32_16x16x32_bf16 v[2:5], v[118:121], v[188:191], v[2:5]
	v_mfma_f32_16x16x32_bf16 v[30:33], v[102:105], v[70:73], v[30:33]
	v_mfma_f32_16x16x32_bf16 v[26:29], v[118:121], v[70:73], v[26:29]
	v_mfma_f32_16x16x32_bf16 v[22:25], v[110:113], v[94:97], v[22:25]
	v_mfma_f32_16x16x32_bf16 v[18:21], v[208:211], v[94:97], v[18:21]
	v_mfma_f32_16x16x32_bf16 v[14:17], v[102:105], v[180:183], v[14:17]
	v_mfma_f32_16x16x32_bf16 v[10:13], v[118:121], v[180:183], v[10:13]
	v_mfma_f32_16x16x32_bf16 v[6:9], v[110:113], v[196:199], v[6:9]
	v_mfma_f32_16x16x32_bf16 v[2:5], v[208:211], v[196:199], v[2:5]
	v_mfma_f32_16x16x32_bf16 v[152:155], v[110:113], v[78:81], v[30:33]
	v_mfma_f32_16x16x32_bf16 v[156:159], v[208:211], v[78:81], v[26:29]
	v_mfma_f32_16x16x32_bf16 v[160:163], v[110:113], v[184:187], v[14:17]
	v_mfma_f32_16x16x32_bf16 v[164:167], v[208:211], v[184:187], v[10:13]
	s_barrier
	s_setprio 0
	s_nop 0
	ds_read_b128 v[10:13], v145
	ds_read_b128 v[14:17], v145 offset:1024
	ds_read_b128 v[180:183], v145 offset:2048
	ds_read_b128 v[144:147], v145 offset:3072
	ds_read_b128 v[26:29], v141 offset:32768
	ds_read_b128 v[30:33], v141 offset:33792
	ds_read_b128 v[42:45], v139 offset:32768
	ds_read_b128 v[46:49], v139 offset:33792
	ds_read_b128 v[184:187], v137 offset:32768
	ds_read_b128 v[188:191], v137 offset:33792
	ds_read_b128 v[196:199], v135 offset:32768
	ds_read_b128 v[208:211], v135 offset:33792
	s_waitcnt vmcnt(2)
	s_setprio 1
	s_barrier
	s_waitcnt lgkmcnt(0)
	v_mfma_f32_16x16x32_bf16 v[70:73], v[10:13], v[26:29], v[126:129]
	v_mfma_f32_16x16x32_bf16 v[126:129], v[14:17], v[30:33], v[70:73]
	v_mfma_f32_16x16x32_bf16 v[70:73], v[180:183], v[26:29], v[122:125]
	v_mfma_f32_16x16x32_bf16 v[118:121], v[144:147], v[30:33], v[70:73]
	v_mfma_f32_16x16x32_bf16 v[70:73], v[10:13], v[42:45], v[130:133]
	v_mfma_f32_16x16x32_bf16 v[110:113], v[14:17], v[46:49], v[70:73]
	v_mfma_f32_16x16x32_bf16 v[70:73], v[180:183], v[42:45], v[114:117]
	v_mfma_f32_16x16x32_bf16 v[102:105], v[144:147], v[46:49], v[70:73]
	v_mfma_f32_16x16x32_bf16 v[70:73], v[10:13], v[184:187], v[148:151]
	v_mfma_f32_16x16x32_bf16 v[94:97], v[14:17], v[188:191], v[70:73]
	v_mfma_f32_16x16x32_bf16 v[70:73], v[180:183], v[184:187], v[106:109]
	v_mfma_f32_16x16x32_bf16 v[86:89], v[144:147], v[188:191], v[70:73]
	v_mfma_f32_16x16x32_bf16 v[70:73], v[10:13], v[196:199], v[204:207]
	v_mfma_f32_16x16x32_bf16 v[78:81], v[14:17], v[208:211], v[70:73]
	v_mfma_f32_16x16x32_bf16 v[70:73], v[180:183], v[196:199], v[98:101]
	v_mfma_f32_16x16x32_bf16 v[70:73], v[144:147], v[208:211], v[70:73]
	s_barrier
;   #define LDA(dst,b,h) for(int m=0;m<4;++m)for(int k=0;k<2;++k) \
;     dst[m][k]=*reinterpret_cast<const bf16x8*>((char*)SA(b,h)+lds_byte(wr*64+m*16+fr,k*32+fq*8))
;   #define LDB(dst,b,h) for(int n=0;n<2;++n)for(int k=0;k<2;++k) \
;     dst[n][k]=*reinterpret_cast<const bf16x8*>((char*)SB(b,h)+lds_byte(wc*32+n*16+fr,k*32+fq*8))
;   #define MMA(ai,bj,At,Bt_) do{__builtin_amdgcn_s_setprio(1); \
;     for(int m=0;m<4;++m)for(int n=0;n<2;++n)for(int k=0;k<2;++k) \
;       acc[ai][bj][m][n]=__builtin_amdgcn_mfma_f32_16x16x32_bf16(Bt_[n][k],At[m][k],acc[ai][bj][m][n],0,0,0); \
;     __builtin_amdgcn_s_setprio(0);}while(0)
;   #define WAIT_V(n) asm volatile("s_waitcnt vmcnt(" #n ")":::"memory")
;   #define WAIT_L(n) asm volatile("s_waitcnt lgkmcnt(" #n ")":::"memory")
;   #define BAR __builtin_amdgcn_s_barrier()
; template <bool TWO, class MID> ...
;     ...
;   { LDB(B0,1,0); LDA(At,1,0); WAIT_V(2); BAR; WAIT_L(0); MMA(0,0,At,B0); BAR;
;     LDB(B1,1,1); WAIT_V(0); BAR; WAIT_L(0); MMA(0,1,At,B1); BAR;
;     LDA(At,1,1); BAR; WAIT_L(0); MMA(1,0,At,B0); MMA(1,1,At,B1); BAR; }
;   if(wr==0)BAR;
	s_setprio 0
	ds_read_b128 v[130:133], v143
	ds_read_b128 v[148:151], v143 offset:1024
	ds_read_b128 v[204:207], v143 offset:2048
	ds_read_b128 v[220:223], v143 offset:3072
	s_waitcnt vmcnt(0)
	s_setprio 1
	s_barrier
	s_waitcnt lgkmcnt(0)
	v_mfma_f32_16x16x32_bf16 v[98:101], v[130:133], v[26:29], v[212:215]
	v_mfma_f32_16x16x32_bf16 v[26:29], v[204:207], v[26:29], v[90:93]
	v_mfma_f32_16x16x32_bf16 v[114:117], v[220:223], v[30:33], v[26:29]
	v_mfma_f32_16x16x32_bf16 v[26:29], v[130:133], v[42:45], v[168:171]
	v_mfma_f32_16x16x32_bf16 v[106:109], v[148:151], v[46:49], v[26:29]
	v_mfma_f32_16x16x32_bf16 v[26:29], v[204:207], v[42:45], v[82:85]
	v_mfma_f32_16x16x32_bf16 v[122:125], v[148:151], v[30:33], v[98:101]
	v_mfma_f32_16x16x32_bf16 v[98:101], v[220:223], v[46:49], v[26:29]
	v_mfma_f32_16x16x32_bf16 v[26:29], v[130:133], v[184:187], v[172:175]
	v_mfma_f32_16x16x32_bf16 v[90:93], v[148:151], v[188:191], v[26:29]
	v_mfma_f32_16x16x32_bf16 v[26:29], v[204:207], v[184:187], v[74:77]
	v_mfma_f32_16x16x32_bf16 v[82:85], v[220:223], v[188:191], v[26:29]
	v_mfma_f32_16x16x32_bf16 v[26:29], v[130:133], v[196:199], v[176:179]
	v_mfma_f32_16x16x32_bf16 v[74:77], v[148:151], v[208:211], v[26:29]
	v_mfma_f32_16x16x32_bf16 v[26:29], v[204:207], v[196:199], v[66:69]
	v_mfma_f32_16x16x32_bf16 v[66:69], v[220:223], v[208:211], v[26:29]
	s_barrier
	s_setprio 0
	ds_read_b128 v[168:171], v141 offset:49152
	ds_read_b128 v[140:143], v141 offset:50176
	ds_read_b128 v[172:175], v139 offset:49152
	ds_read_b128 v[176:179], v139 offset:50176
	ds_read_b128 v[184:187], v137 offset:49152
	ds_read_b128 v[136:139], v137 offset:50176
	ds_read_b128 v[188:191], v135 offset:49152
	ds_read_b128 v[196:199], v135 offset:50176
	s_setprio 1
	s_barrier
	s_waitcnt lgkmcnt(0)
	v_mfma_f32_16x16x32_bf16 v[26:29], v[10:13], v[168:171], v[62:65]
	v_mfma_f32_16x16x32_bf16 v[62:65], v[14:17], v[140:143], v[26:29]
	v_mfma_f32_16x16x32_bf16 v[26:29], v[180:183], v[168:171], v[58:61]
	v_mfma_f32_16x16x32_bf16 v[58:61], v[144:147], v[140:143], v[26:29]
	v_mfma_f32_16x16x32_bf16 v[26:29], v[10:13], v[172:175], v[54:57]
	v_mfma_f32_16x16x32_bf16 v[46:49], v[14:17], v[176:179], v[26:29]
	v_mfma_f32_16x16x32_bf16 v[26:29], v[180:183], v[172:175], v[50:53]
	v_mfma_f32_16x16x32_bf16 v[42:45], v[144:147], v[176:179], v[26:29]
	v_mfma_f32_16x16x32_bf16 v[26:29], v[10:13], v[184:187], v[200:203]
	v_mfma_f32_16x16x32_bf16 v[10:13], v[10:13], v[188:191], v[38:41]
	v_mfma_f32_16x16x32_bf16 v[30:33], v[14:17], v[136:139], v[26:29]
	v_mfma_f32_16x16x32_bf16 v[26:29], v[180:183], v[184:187], v[216:219]
	v_mfma_f32_16x16x32_bf16 v[14:17], v[14:17], v[196:199], v[10:13]
	v_mfma_f32_16x16x32_bf16 v[10:13], v[180:183], v[188:191], v[34:37]
	v_mfma_f32_16x16x32_bf16 v[26:29], v[144:147], v[136:139], v[26:29]
	v_mfma_f32_16x16x32_bf16 v[10:13], v[144:147], v[196:199], v[10:13]
	s_setprio 0
	s_setprio 1
	v_mfma_f32_16x16x32_bf16 v[34:37], v[130:133], v[168:171], v[152:155]
	v_mfma_f32_16x16x32_bf16 v[54:57], v[148:151], v[140:143], v[34:37]
	v_mfma_f32_16x16x32_bf16 v[34:37], v[204:207], v[168:171], v[156:159]
	v_mfma_f32_16x16x32_bf16 v[18:21], v[204:207], v[172:175], v[18:21]
	v_mfma_f32_16x16x32_bf16 v[50:53], v[220:223], v[140:143], v[34:37]
	v_mfma_f32_16x16x32_bf16 v[22:25], v[130:133], v[172:175], v[22:25]
	v_mfma_f32_16x16x32_bf16 v[34:37], v[220:223], v[176:179], v[18:21]
	v_mfma_f32_16x16x32_bf16 v[18:21], v[130:133], v[184:187], v[160:163]
	v_mfma_f32_16x16x32_bf16 v[38:41], v[148:151], v[176:179], v[22:25]
	v_mfma_f32_16x16x32_bf16 v[22:25], v[148:151], v[136:139], v[18:21]
	v_mfma_f32_16x16x32_bf16 v[18:21], v[204:207], v[184:187], v[164:167]
	v_mfma_f32_16x16x32_bf16 v[6:9], v[130:133], v[188:191], v[6:9]
	v_mfma_f32_16x16x32_bf16 v[2:5], v[204:207], v[188:191], v[2:5]
	v_mfma_f32_16x16x32_bf16 v[18:21], v[220:223], v[136:139], v[18:21]
	v_mfma_f32_16x16x32_bf16 v[6:9], v[148:151], v[196:199], v[6:9]
	v_mfma_f32_16x16x32_bf16 v[2:5], v[220:223], v[196:199], v[2:5]
	s_setprio 0
	v_cmp_gt_u32_e32 vcc, s30, v1
	s_barrier
	s_and_saveexec_b64 s[4:5], vcc
	s_cbranch_execz .LBB0_565
	s_barrier

;   #define LDA(dst,b,h) for(int m=0;m<4;++m)for(int k=0;k<2;++k) \
;     dst[m][k]=*reinterpret_cast<const bf16x8*>((char*)SA(b,h)+lds_byte(wr*64+m*16+fr,k*32+fq*8))
;   #define LDB(dst,b,h) for(int n=0;n<2;++n)for(int k=0;k<2;++k) \
;     dst[n][k]=*reinterpret_cast<const bf16x8*>((char*)SB(b,h)+lds_byte(wc*32+n*16+fr,k*32+fq*8))
;   #define MMA(ai,bj,At,Bt_) do{__builtin_amdgcn_s_setprio(1); \
;     for(int m=0;m<4;++m)for(int n=0;n<2;++n)for(int k=0;k<2;++k) \
;       acc[ai][bj][m][n]=__builtin_amdgcn_mfma_f32_16x16x32_bf16(Bt_[n][k],At[m][k],acc[ai][bj][m][n],0,0,0); \
;     __builtin_amdgcn_s_setprio(0);}while(0)
;   #define WAIT_V(n) asm volatile("s_waitcnt vmcnt(" #n ")":::"memory")
;   #define WAIT_L(n) asm volatile("s_waitcnt lgkmcnt(" #n ")":::"memory")
;   #define BAR __builtin_amdgcn_s_barrier()
;   #define SCHED __builtin_amdgcn_sched_barrier(0)
; template <bool TWO, class MID> ...
;     ...
;     LDB(B0,0,0); SCHED; LDA(At,0,0); STAGE_A(SA(1,1),1,t+1);
;     WAIT_L(8); BAR; WAIT_L(0); MMA(0,0,At,B0); BAR; SCHED;
;     LDB(B1,0,1); STAGE_B(SB(0,0),0,t+2);
;     BAR; WAIT_L(0); MMA(0,1,At,B1); BAR;
;     LDA(At,0,1); STAGE_A(SA(0,0),0,t+2);
;     BAR; WAIT_L(0); MMA(1,0,At,B0); BAR; SCHED;
;     STAGE_B(SB(0,1),1,t+2);
;     WAIT_V(6); BAR; MMA(1,1,At,B1); BAR;
.LBB0_620:
	ds_read_b128 v[166:169], v149
	ds_read_b128 v[170:173], v149 offset:1024
	ds_read_b128 v[174:177], v149 offset:2048
	ds_read_b128 v[178:181], v149 offset:3072
	ds_read_b128 v[182:185], v141
	ds_read_b128 v[186:189], v141 offset:1024
	ds_read_b128 v[190:193], v139
	ds_read_b128 v[196:199], v139 offset:1024
	ds_read_b128 v[200:203], v137
	ds_read_b128 v[204:207], v137 offset:1024
	ds_read_b128 v[208:211], v135
	ds_read_b128 v[212:215], v135 offset:1024
	s_add_u32 s15, s0, s16
	s_addc_u32 s18, s1, s17
	s_add_u32 m0, s98, 0xc000
	s_add_u32 s24, s15, 0x10200080
	s_addc_u32 s25, s18, 0
	global_load_lds_dwordx4 v132, s[24:25]
	s_add_u32 m0, s98, 0xe000
	s_setprio 1
	global_load_lds_dwordx4 v130, s[24:25]
	s_waitcnt lgkmcnt(8)
	s_barrier
	s_waitcnt lgkmcnt(0)
	v_mfma_f32_16x16x32_bf16 v[126:129], v[166:169], v[182:185], v[126:129]
	v_mfma_f32_16x16x32_bf16 v[122:125], v[174:177], v[182:185], v[122:125]
	v_mfma_f32_16x16x32_bf16 v[118:121], v[166:169], v[190:193], v[118:121]
	v_mfma_f32_16x16x32_bf16 v[114:117], v[174:177], v[190:193], v[114:117]
	v_mfma_f32_16x16x32_bf16 v[110:113], v[166:169], v[200:203], v[110:113]
	v_mfma_f32_16x16x32_bf16 v[106:109], v[174:177], v[200:203], v[106:109]
	v_mfma_f32_16x16x32_bf16 v[102:105], v[166:169], v[208:211], v[102:105]
	v_mfma_f32_16x16x32_bf16 v[98:101], v[174:177], v[208:211], v[98:101]
	v_mfma_f32_16x16x32_bf16 v[126:129], v[170:173], v[186:189], v[126:129]
	v_mfma_f32_16x16x32_bf16 v[122:125], v[178:181], v[186:189], v[122:125]
	v_mfma_f32_16x16x32_bf16 v[118:121], v[170:173], v[196:199], v[118:121]
	v_mfma_f32_16x16x32_bf16 v[114:117], v[178:181], v[196:199], v[114:117]
	v_mfma_f32_16x16x32_bf16 v[110:113], v[170:173], v[204:207], v[110:113]
	v_mfma_f32_16x16x32_bf16 v[106:109], v[178:181], v[204:207], v[106:109]
	v_mfma_f32_16x16x32_bf16 v[102:105], v[170:173], v[212:215], v[102:105]
	v_mfma_f32_16x16x32_bf16 v[98:101], v[178:181], v[212:215], v[98:101]
	s_barrier
	s_setprio 0
	s_add_u32 s19, s0, s4
	ds_read_b128 v[216:219], v147
	ds_read_b128 v[220:223], v147 offset:1024
	ds_read_b128 v[224:227], v147 offset:2048
	ds_read_b128 v[228:231], v147 offset:3072
	s_addc_u32 s24, s1, s5
	s_add_u32 m0, s98, 0x10000
	s_add_u32 s26, s19, 0x5c00100
	s_addc_u32 s27, s24, 0
	global_load_lds_dwordx4 v132, s[26:27]
	s_add_u32 m0, s98, 0x12000
	s_setprio 1
	global_load_lds_dwordx4 v130, s[26:27]
	s_barrier
	s_waitcnt lgkmcnt(0)
	v_mfma_f32_16x16x32_bf16 v[94:97], v[216:219], v[182:185], v[94:97]
	v_mfma_f32_16x16x32_bf16 v[90:93], v[224:227], v[182:185], v[90:93]
	v_mfma_f32_16x16x32_bf16 v[86:89], v[216:219], v[190:193], v[86:89]
	v_mfma_f32_16x16x32_bf16 v[82:85], v[224:227], v[190:193], v[82:85]
	v_mfma_f32_16x16x32_bf16 v[78:81], v[216:219], v[200:203], v[78:81]
	v_mfma_f32_16x16x32_bf16 v[74:77], v[224:227], v[200:203], v[74:77]
	v_mfma_f32_16x16x32_bf16 v[70:73], v[216:219], v[208:211], v[70:73]
	v_mfma_f32_16x16x32_bf16 v[66:69], v[224:227], v[208:211], v[66:69]
	v_mfma_f32_16x16x32_bf16 v[94:97], v[220:223], v[186:189], v[94:97]
	v_mfma_f32_16x16x32_bf16 v[90:93], v[228:231], v[186:189], v[90:93]
	v_mfma_f32_16x16x32_bf16 v[86:89], v[220:223], v[196:199], v[86:89]
	v_mfma_f32_16x16x32_bf16 v[82:85], v[228:231], v[196:199], v[82:85]
	v_mfma_f32_16x16x32_bf16 v[78:81], v[220:223], v[204:207], v[78:81]
	v_mfma_f32_16x16x32_bf16 v[74:77], v[228:231], v[204:207], v[74:77]
	v_mfma_f32_16x16x32_bf16 v[70:73], v[220:223], v[212:215], v[70:73]
	v_mfma_f32_16x16x32_bf16 v[66:69], v[228:231], v[212:215], v[66:69]
	s_barrier
	s_setprio 0
	ds_read_b128 v[182:185], v141 offset:16384
	ds_read_b128 v[186:189], v141 offset:17408
	ds_read_b128 v[190:193], v139 offset:16384
	ds_read_b128 v[196:199], v139 offset:17408
	ds_read_b128 v[200:203], v137 offset:16384
	ds_read_b128 v[204:207], v137 offset:17408
	ds_read_b128 v[208:211], v135 offset:16384
	ds_read_b128 v[212:215], v135 offset:17408
	s_add_u32 m0, s98, 0x0
	s_add_u32 s26, s15, 0x10000100
	s_addc_u32 s27, s18, 0
	global_load_lds_dwordx4 v132, s[26:27]
	s_add_u32 m0, s98, 0x2000
	s_setprio 1
	global_load_lds_dwordx4 v130, s[26:27]
	s_barrier
	s_waitcnt lgkmcnt(0)
	v_mfma_f32_16x16x32_bf16 v[62:65], v[166:169], v[182:185], v[62:65]
	v_mfma_f32_16x16x32_bf16 v[58:61], v[174:177], v[182:185], v[58:61]
	v_mfma_f32_16x16x32_bf16 v[54:57], v[166:169], v[190:193], v[54:57]
	v_mfma_f32_16x16x32_bf16 v[50:53], v[174:177], v[190:193], v[50:53]
	v_mfma_f32_16x16x32_bf16 v[46:49], v[166:169], v[200:203], v[46:49]
	v_mfma_f32_16x16x32_bf16 v[42:45], v[174:177], v[200:203], v[42:45]
	v_mfma_f32_16x16x32_bf16 v[38:41], v[166:169], v[208:211], v[38:41]
	v_mfma_f32_16x16x32_bf16 v[34:37], v[174:177], v[208:211], v[34:37]
	v_mfma_f32_16x16x32_bf16 v[62:65], v[170:173], v[186:189], v[62:65]
	v_mfma_f32_16x16x32_bf16 v[58:61], v[178:181], v[186:189], v[58:61]
	v_mfma_f32_16x16x32_bf16 v[54:57], v[170:173], v[196:199], v[54:57]
	v_mfma_f32_16x16x32_bf16 v[50:53], v[178:181], v[196:199], v[50:53]
	v_mfma_f32_16x16x32_bf16 v[46:49], v[170:173], v[204:207], v[46:49]
	v_mfma_f32_16x16x32_bf16 v[42:45], v[178:181], v[204:207], v[42:45]
	v_mfma_f32_16x16x32_bf16 v[38:41], v[170:173], v[212:215], v[38:41]
	v_mfma_f32_16x16x32_bf16 v[34:37], v[178:181], v[212:215], v[34:37]
	s_barrier
	s_setprio 0
	s_add_u32 m0, s98, 0x14000
	s_add_u32 s26, s19, 0x5e00100
	s_addc_u32 s27, s24, 0
	global_load_lds_dwordx4 v132, s[26:27]
	s_add_u32 m0, s98, 0x16000
	s_setprio 1
	global_load_lds_dwordx4 v130, s[26:27]
	s_waitcnt vmcnt(6)
	s_barrier
;   #define LDA(dst,b,h) for(int m=0;m<4;++m)for(int k=0;k<2;++k) \
;     dst[m][k]=*reinterpret_cast<const bf16x8*>((char*)SA(b,h)+lds_byte(wr*64+m*16+fr,k*32+fq*8))
;   #define LDB(dst,b,h) for(int n=0;n<2;++n)for(int k=0;k<2;++k) \
;     dst[n][k]=*reinterpret_cast<const bf16x8*>((char*)SB(b,h)+lds_byte(wc*32+n*16+fr,k*32+fq*8))
;   #define MMA(ai,bj,At,Bt_) do{__builtin_amdgcn_s_setprio(1); \
;     for(int m=0;m<4;++m)for(int n=0;n<2;++n)for(int k=0;k<2;++k) \
;       acc[ai][bj][m][n]=__builtin_amdgcn_mfma_f32_16x16x32_bf16(Bt_[n][k],At[m][k],acc[ai][bj][m][n],0,0,0); \
;     __builtin_amdgcn_s_setprio(0);}while(0)
;   #define WAIT_V(n) asm volatile("s_waitcnt vmcnt(" #n ")":::"memory")
;   #define WAIT_L(n) asm volatile("s_waitcnt lgkmcnt(" #n ")":::"memory")
;   #define BAR __builtin_amdgcn_s_barrier()
;   #define SCHED __builtin_amdgcn_sched_barrier(0)
; template <bool TWO, class MID> ...
;     ...
;     WAIT_V(6); BAR; MMA(1,1,At,B1); BAR;
;     LDB(B0,1,0); SCHED; LDA(At,1,0); STAGE_A(SA(0,1),1,t+2);
;     WAIT_L(8); BAR; WAIT_L(0); MMA(0,0,At,B0); BAR; SCHED;
;     LDB(B1,1,1); STAGE_B(SB(1,0),0,t+3);
;     BAR; WAIT_L(0); MMA(0,1,At,B1); BAR;
;     LDA(At,1,1); STAGE_A(SA(1,0),0,t+3);
	v_mfma_f32_16x16x32_bf16 v[30:33], v[216:219], v[182:185], v[30:33]
	v_mfma_f32_16x16x32_bf16 v[26:29], v[224:227], v[182:185], v[26:29]
	v_mfma_f32_16x16x32_bf16 v[22:25], v[216:219], v[190:193], v[22:25]
	v_mfma_f32_16x16x32_bf16 v[18:21], v[224:227], v[190:193], v[18:21]
	v_mfma_f32_16x16x32_bf16 v[14:17], v[216:219], v[200:203], v[14:17]
	v_mfma_f32_16x16x32_bf16 v[10:13], v[224:227], v[200:203], v[10:13]
	v_mfma_f32_16x16x32_bf16 v[6:9], v[216:219], v[208:211], v[6:9]
	v_mfma_f32_16x16x32_bf16 v[2:5], v[224:227], v[208:211], v[2:5]
	v_mfma_f32_16x16x32_bf16 v[30:33], v[220:223], v[186:189], v[30:33]
	v_mfma_f32_16x16x32_bf16 v[26:29], v[228:231], v[186:189], v[26:29]
	v_mfma_f32_16x16x32_bf16 v[22:25], v[220:223], v[196:199], v[22:25]
	v_mfma_f32_16x16x32_bf16 v[18:21], v[228:231], v[196:199], v[18:21]
	v_mfma_f32_16x16x32_bf16 v[14:17], v[220:223], v[204:207], v[14:17]
	v_mfma_f32_16x16x32_bf16 v[10:13], v[228:231], v[204:207], v[10:13]
	v_mfma_f32_16x16x32_bf16 v[6:9], v[220:223], v[212:215], v[6:9]
	v_mfma_f32_16x16x32_bf16 v[2:5], v[228:231], v[212:215], v[2:5]
	s_barrier
	s_setprio 0
	ds_read_b128 v[166:169], v145
	ds_read_b128 v[170:173], v145 offset:1024
	ds_read_b128 v[174:177], v145 offset:2048
	ds_read_b128 v[178:181], v145 offset:3072
	ds_read_b128 v[182:185], v141 offset:32768
	ds_read_b128 v[186:189], v141 offset:33792
	ds_read_b128 v[190:193], v139 offset:32768
	ds_read_b128 v[196:199], v139 offset:33792
	ds_read_b128 v[200:203], v137 offset:32768
	ds_read_b128 v[204:207], v137 offset:33792
	ds_read_b128 v[208:211], v135 offset:32768
	ds_read_b128 v[212:215], v135 offset:33792
	s_add_u32 m0, s98, 0x4000
	s_add_u32 s26, s15, 0x10200100
	s_addc_u32 s27, s18, 0
	global_load_lds_dwordx4 v132, s[26:27]
	s_add_u32 m0, s98, 0x6000
	s_setprio 1
	global_load_lds_dwordx4 v130, s[26:27]
	s_waitcnt lgkmcnt(8)
	s_barrier
	s_waitcnt lgkmcnt(0)
	v_mfma_f32_16x16x32_bf16 v[126:129], v[166:169], v[182:185], v[126:129]
	v_mfma_f32_16x16x32_bf16 v[122:125], v[174:177], v[182:185], v[122:125]
	v_mfma_f32_16x16x32_bf16 v[118:121], v[166:169], v[190:193], v[118:121]
	v_mfma_f32_16x16x32_bf16 v[114:117], v[174:177], v[190:193], v[114:117]
	v_mfma_f32_16x16x32_bf16 v[110:113], v[166:169], v[200:203], v[110:113]
	v_mfma_f32_16x16x32_bf16 v[106:109], v[174:177], v[200:203], v[106:109]
	v_mfma_f32_16x16x32_bf16 v[102:105], v[166:169], v[208:211], v[102:105]
	v_mfma_f32_16x16x32_bf16 v[98:101], v[174:177], v[208:211], v[98:101]
	v_mfma_f32_16x16x32_bf16 v[126:129], v[170:173], v[186:189], v[126:129]
	v_mfma_f32_16x16x32_bf16 v[122:125], v[178:181], v[186:189], v[122:125]
	v_mfma_f32_16x16x32_bf16 v[118:121], v[170:173], v[196:199], v[118:121]
	v_mfma_f32_16x16x32_bf16 v[114:117], v[178:181], v[196:199], v[114:117]
	v_mfma_f32_16x16x32_bf16 v[110:113], v[170:173], v[204:207], v[110:113]
	v_mfma_f32_16x16x32_bf16 v[106:109], v[178:181], v[204:207], v[106:109]
	v_mfma_f32_16x16x32_bf16 v[102:105], v[170:173], v[212:215], v[102:105]
	v_mfma_f32_16x16x32_bf16 v[98:101], v[178:181], v[212:215], v[98:101]
	s_barrier
	s_setprio 0
	ds_read_b128 v[216:219], v143
	ds_read_b128 v[220:223], v143 offset:1024
	ds_read_b128 v[224:227], v143 offset:2048
	ds_read_b128 v[228:231], v143 offset:3072
	s_add_u32 m0, s98, 0x18000
	s_add_u32 s26, s19, 0x5c00180
	s_addc_u32 s27, s24, 0
	global_load_lds_dwordx4 v132, s[26:27]
	s_add_u32 m0, s98, 0x1a000
	s_setprio 1
	global_load_lds_dwordx4 v130, s[26:27]
	s_barrier
	s_waitcnt lgkmcnt(0)
	v_mfma_f32_16x16x32_bf16 v[94:97], v[216:219], v[182:185], v[94:97]
	v_mfma_f32_16x16x32_bf16 v[90:93], v[224:227], v[182:185], v[90:93]
	v_mfma_f32_16x16x32_bf16 v[86:89], v[216:219], v[190:193], v[86:89]
	v_mfma_f32_16x16x32_bf16 v[82:85], v[224:227], v[190:193], v[82:85]
	v_mfma_f32_16x16x32_bf16 v[78:81], v[216:219], v[200:203], v[78:81]
	v_mfma_f32_16x16x32_bf16 v[74:77], v[224:227], v[200:203], v[74:77]
	v_mfma_f32_16x16x32_bf16 v[70:73], v[216:219], v[208:211], v[70:73]
	v_mfma_f32_16x16x32_bf16 v[66:69], v[224:227], v[208:211], v[66:69]
	v_mfma_f32_16x16x32_bf16 v[94:97], v[220:223], v[186:189], v[94:97]
	v_mfma_f32_16x16x32_bf16 v[90:93], v[228:231], v[186:189], v[90:93]
	v_mfma_f32_16x16x32_bf16 v[86:89], v[220:223], v[196:199], v[86:89]
	v_mfma_f32_16x16x32_bf16 v[82:85], v[228:231], v[196:199], v[82:85]
	v_mfma_f32_16x16x32_bf16 v[78:81], v[220:223], v[204:207], v[78:81]
	v_mfma_f32_16x16x32_bf16 v[74:77], v[228:231], v[204:207], v[74:77]
	v_mfma_f32_16x16x32_bf16 v[70:73], v[220:223], v[212:215], v[70:73]
	v_mfma_f32_16x16x32_bf16 v[66:69], v[228:231], v[212:215], v[66:69]
	s_barrier
	s_setprio 0
	ds_read_b128 v[182:185], v141 offset:49152
	ds_read_b128 v[186:189], v141 offset:50176
	ds_read_b128 v[190:193], v139 offset:49152
	ds_read_b128 v[196:199], v139 offset:50176
	ds_read_b128 v[200:203], v137 offset:49152
	ds_read_b128 v[204:207], v137 offset:50176
	ds_read_b128 v[208:211], v135 offset:49152
	ds_read_b128 v[212:215], v135 offset:50176
	s_add_u32 m0, s98, 0x8000
	s_add_u32 s26, s15, 0x10000180
	s_addc_u32 s27, s18, 0
	global_load_lds_dwordx4 v132, s[26:27]
	s_add_u32 m0, s98, 0xa000
	s_setprio 1
	global_load_lds_dwordx4 v130, s[26:27]
	s_barrier
;   #define LDA(dst,b,h) for(int m=0;m<4;++m)for(int k=0;k<2;++k) \
;     dst[m][k]=*reinterpret_cast<const bf16x8*>((char*)SA(b,h)+lds_byte(wr*64+m*16+fr,k*32+fq*8))
;   #define LDB(dst,b,h) for(int n=0;n<2;++n)for(int k=0;k<2;++k) \
;     dst[n][k]=*reinterpret_cast<const bf16x8*>((char*)SB(b,h)+lds_byte(wc*32+n*16+fr,k*32+fq*8))
;   #define MMA(ai,bj,At,Bt_) do{__builtin_amdgcn_s_setprio(1); \
;     for(int m=0;m<4;++m)for(int n=0;n<2;++n)for(int k=0;k<2;++k) \
;       acc[ai][bj][m][n]=__builtin_amdgcn_mfma_f32_16x16x32_bf16(Bt_[n][k],At[m][k],acc[ai][bj][m][n],0,0,0); \
;     __builtin_amdgcn_s_setprio(0);}while(0)
;   #define WAIT_V(n) asm volatile("s_waitcnt vmcnt(" #n ")":::"memory")
;   #define WAIT_L(n) asm volatile("s_waitcnt lgkmcnt(" #n ")":::"memory")
;   #define BAR __builtin_amdgcn_s_barrier()
;   #define SCHED __builtin_amdgcn_sched_barrier(0)
; template <bool TWO, class MID> ...
;     ...
;     LDA(At,1,1); STAGE_A(SA(1,0),0,t+3);
;     BAR; WAIT_L(0); MMA(1,0,At,B0); BAR; SCHED;
;     STAGE_B(SB(1,1),1,t+3);
;     WAIT_V(6); BAR; MMA(1,1,At,B1); BAR;
;   }
;   { LDB(B0,0,0); LDA(At,0,0); STAGE_A(SA(1,1),1,nt-1);
;     BAR; WAIT_L(0); MMA(0,0,At,B0); BAR;
;     LDB(B1,0,1); BAR; WAIT_L(0); MMA(0,1,At,B1); BAR;
	s_waitcnt lgkmcnt(0)
	v_mfma_f32_16x16x32_bf16 v[62:65], v[166:169], v[182:185], v[62:65]
	v_mfma_f32_16x16x32_bf16 v[58:61], v[174:177], v[182:185], v[58:61]
	v_mfma_f32_16x16x32_bf16 v[54:57], v[166:169], v[190:193], v[54:57]
	v_mfma_f32_16x16x32_bf16 v[50:53], v[174:177], v[190:193], v[50:53]
	v_mfma_f32_16x16x32_bf16 v[46:49], v[166:169], v[200:203], v[46:49]
	v_mfma_f32_16x16x32_bf16 v[42:45], v[174:177], v[200:203], v[42:45]
	v_mfma_f32_16x16x32_bf16 v[38:41], v[166:169], v[208:211], v[38:41]
	v_mfma_f32_16x16x32_bf16 v[34:37], v[174:177], v[208:211], v[34:37]
	v_mfma_f32_16x16x32_bf16 v[62:65], v[170:173], v[186:189], v[62:65]
	v_mfma_f32_16x16x32_bf16 v[58:61], v[178:181], v[186:189], v[58:61]
	v_mfma_f32_16x16x32_bf16 v[54:57], v[170:173], v[196:199], v[54:57]
	v_mfma_f32_16x16x32_bf16 v[50:53], v[178:181], v[196:199], v[50:53]
	v_mfma_f32_16x16x32_bf16 v[46:49], v[170:173], v[204:207], v[46:49]
	v_mfma_f32_16x16x32_bf16 v[42:45], v[178:181], v[204:207], v[42:45]
	v_mfma_f32_16x16x32_bf16 v[38:41], v[170:173], v[212:215], v[38:41]
	v_mfma_f32_16x16x32_bf16 v[34:37], v[178:181], v[212:215], v[34:37]
	s_barrier
	s_setprio 0
	s_add_u32 m0, s98, 0x1c000
	s_add_u32 s18, s19, 0x5e00180
	s_addc_u32 s19, s24, 0
	global_load_lds_dwordx4 v132, s[18:19]
	s_add_u32 m0, s98, 0x1e000
	s_setprio 1
	global_load_lds_dwordx4 v130, s[18:19]
	s_waitcnt vmcnt(6)
	s_barrier
	v_mfma_f32_16x16x32_bf16 v[30:33], v[216:219], v[182:185], v[30:33]
	v_mfma_f32_16x16x32_bf16 v[26:29], v[224:227], v[182:185], v[26:29]
	v_mfma_f32_16x16x32_bf16 v[22:25], v[216:219], v[190:193], v[22:25]
	v_mfma_f32_16x16x32_bf16 v[18:21], v[224:227], v[190:193], v[18:21]
	v_mfma_f32_16x16x32_bf16 v[14:17], v[216:219], v[200:203], v[14:17]
	v_mfma_f32_16x16x32_bf16 v[10:13], v[224:227], v[200:203], v[10:13]
	v_mfma_f32_16x16x32_bf16 v[6:9], v[216:219], v[208:211], v[6:9]
	v_mfma_f32_16x16x32_bf16 v[2:5], v[224:227], v[208:211], v[2:5]
	v_mfma_f32_16x16x32_bf16 v[30:33], v[220:223], v[186:189], v[30:33]
	v_mfma_f32_16x16x32_bf16 v[26:29], v[228:231], v[186:189], v[26:29]
	v_mfma_f32_16x16x32_bf16 v[22:25], v[220:223], v[196:199], v[22:25]
	v_mfma_f32_16x16x32_bf16 v[18:21], v[228:231], v[196:199], v[18:21]
	v_mfma_f32_16x16x32_bf16 v[14:17], v[220:223], v[204:207], v[14:17]
	v_mfma_f32_16x16x32_bf16 v[10:13], v[228:231], v[204:207], v[10:13]
	v_mfma_f32_16x16x32_bf16 v[6:9], v[220:223], v[212:215], v[6:9]
	v_mfma_f32_16x16x32_bf16 v[2:5], v[228:231], v[212:215], v[2:5]
	s_setprio 0
	s_add_i32 s14, s14, 2
	s_add_u32 s0, s0, 0x100
	s_addc_u32 s1, s1, 0
	s_cmpk_lt_u32 s14, 0x7c
	s_barrier
	s_cbranch_scc1 .LBB0_620
	ds_read_b128 v[152:155], v149
	ds_read_b128 v[156:159], v149 offset:1024
	ds_read_b128 v[160:163], v149 offset:2048
	ds_read_b128 v[164:167], v149 offset:3072
	ds_read_b128 v[168:171], v141
	ds_read_b128 v[172:175], v141 offset:1024
	ds_read_b128 v[176:179], v139
	ds_read_b128 v[180:183], v139 offset:1024
	ds_read_b128 v[184:187], v137
	ds_read_b128 v[188:191], v137 offset:1024
	ds_read_b128 v[196:199], v135
	ds_read_b128 v[200:203], v135 offset:1024
	s_add_u32 s0, s12, 0x203f80
	s_addc_u32 s1, s13, 0
	v_lshl_add_u64 v[132:133], s[0:1], 0, v[132:133]
	v_readfirstlane_b32 s12, v148
	s_mov_b32 m0, s12
	global_load_lds_dwordx4 v[132:133], off
	v_lshl_add_u64 v[130:131], s[0:1], 0, v[130:131]
	v_readfirstlane_b32 s0, v150
	s_mov_b32 m0, s0
	global_load_lds_dwordx4 v[130:131], off
	s_setprio 1
	s_barrier
	s_waitcnt lgkmcnt(0)
	v_mfma_f32_16x16x32_bf16 v[126:129], v[152:155], v[168:171], v[126:129]
	v_mfma_f32_16x16x32_bf16 v[122:125], v[160:163], v[168:171], v[122:125]
	v_mfma_f32_16x16x32_bf16 v[118:121], v[152:155], v[176:179], v[118:121]
	v_mfma_f32_16x16x32_bf16 v[114:117], v[160:163], v[176:179], v[114:117]
	v_mfma_f32_16x16x32_bf16 v[102:105], v[152:155], v[196:199], v[102:105]
	v_mfma_f32_16x16x32_bf16 v[98:101], v[160:163], v[196:199], v[98:101]
	v_mfma_f32_16x16x32_bf16 v[126:129], v[156:159], v[172:175], v[126:129]
	v_mfma_f32_16x16x32_bf16 v[122:125], v[164:167], v[172:175], v[122:125]
	v_mfma_f32_16x16x32_bf16 v[118:121], v[156:159], v[180:183], v[118:121]
	v_mfma_f32_16x16x32_bf16 v[114:117], v[164:167], v[180:183], v[114:117]
	v_mfma_f32_16x16x32_bf16 v[110:113], v[152:155], v[184:187], v[110:113]
	v_mfma_f32_16x16x32_bf16 v[106:109], v[160:163], v[184:187], v[106:109]
	v_mfma_f32_16x16x32_bf16 v[102:105], v[156:159], v[200:203], v[102:105]
	v_mfma_f32_16x16x32_bf16 v[98:101], v[164:167], v[200:203], v[98:101]
	v_mfma_f32_16x16x32_bf16 v[130:133], v[156:159], v[188:191], v[110:113]
	v_mfma_f32_16x16x32_bf16 v[148:151], v[164:167], v[188:191], v[106:109]
	s_barrier
	s_setprio 0
	s_nop 0
	ds_read_b128 v[106:109], v147
	ds_read_b128 v[110:113], v147 offset:1024
	ds_read_b128 v[204:207], v147 offset:2048
	ds_read_b128 v[208:211], v147 offset:3072
	s_setprio 1
	s_barrier
	s_waitcnt lgkmcnt(0)
	v_mfma_f32_16x16x32_bf16 v[86:89], v[106:109], v[176:179], v[86:89]
	v_mfma_f32_16x16x32_bf16 v[82:85], v[204:207], v[176:179], v[82:85]
	v_mfma_f32_16x16x32_bf16 v[70:73], v[106:109], v[196:199], v[70:73]
	v_mfma_f32_16x16x32_bf16 v[66:69], v[204:207], v[196:199], v[66:69]
	v_mfma_f32_16x16x32_bf16 v[94:97], v[106:109], v[168:171], v[94:97]
	v_mfma_f32_16x16x32_bf16 v[90:93], v[204:207], v[168:171], v[90:93]
	v_mfma_f32_16x16x32_bf16 v[86:89], v[110:113], v[180:183], v[86:89]
	v_mfma_f32_16x16x32_bf16 v[82:85], v[208:211], v[180:183], v[82:85]
	v_mfma_f32_16x16x32_bf16 v[78:81], v[106:109], v[184:187], v[78:81]
	v_mfma_f32_16x16x32_bf16 v[74:77], v[204:207], v[184:187], v[74:77]
	v_mfma_f32_16x16x32_bf16 v[70:73], v[110:113], v[200:203], v[70:73]
	v_mfma_f32_16x16x32_bf16 v[66:69], v[208:211], v[200:203], v[66:69]
	v_mfma_f32_16x16x32_bf16 v[212:215], v[110:113], v[172:175], v[94:97]
	v_mfma_f32_16x16x32_bf16 v[168:171], v[208:211], v[172:175], v[90:93]
	v_mfma_f32_16x16x32_bf16 v[172:175], v[110:113], v[188:191], v[78:81]
	v_mfma_f32_16x16x32_bf16 v[176:179], v[208:211], v[188:191], v[74:77]
	s_barrier
;   #define LDA(dst,b,h) for(int m=0;m<4;++m)for(int k=0;k<2;++k) \
;     dst[m][k]=*reinterpret_cast<const bf16x8*>((char*)SA(b,h)+lds_byte(wr*64+m*16+fr,k*32+fq*8))
;   #define LDB(dst,b,h) for(int n=0;n<2;++n)for(int k=0;k<2;++k) \
;     dst[n][k]=*reinterpret_cast<const bf16x8*>((char*)SB(b,h)+lds_byte(wc*32+n*16+fr,k*32+fq*8))
;   #define MMA(ai,bj,At,Bt_) do{__builtin_amdgcn_s_setprio(1); \
;     for(int m=0;m<4;++m)for(int n=0;n<2;++n)for(int k=0;k<2;++k) \
;       acc[ai][bj][m][n]=__builtin_amdgcn_mfma_f32_16x16x32_bf16(Bt_[n][k],At[m][k],acc[ai][bj][m][n],0,0,0); \
;     __builtin_amdgcn_s_setprio(0);}while(0)
;   #define WAIT_V(n) asm volatile("s_waitcnt vmcnt(" #n ")":::"memory")
;   #define WAIT_L(n) asm volatile("s_waitcnt lgkmcnt(" #n ")":::"memory")
;   #define BAR __builtin_amdgcn_s_barrier()
; template <bool TWO, class MID> ...
;     ...
;     LDA(At,0,1); WAIT_V(4); BAR; WAIT_L(0); MMA(1,0,At,B0); MMA(1,1,At,B1); BAR; }
;   { LDB(B0,1,0); LDA(At,1,0); WAIT_V(2); BAR; WAIT_L(0); MMA(0,0,At,B0); BAR;
;     LDB(B1,1,1); WAIT_V(0); BAR; WAIT_L(0); MMA(0,1,At,B1); BAR;
	s_setprio 0
	s_nop 0
	ds_read_b128 v[74:77], v141 offset:16384
	ds_read_b128 v[78:81], v141 offset:17408
	ds_read_b128 v[90:93], v139 offset:16384
	ds_read_b128 v[94:97], v139 offset:17408
	ds_read_b128 v[180:183], v137 offset:16384
	ds_read_b128 v[184:187], v137 offset:17408
	ds_read_b128 v[188:191], v135 offset:16384
	ds_read_b128 v[196:199], v135 offset:17408
	s_waitcnt vmcnt(4)
	s_setprio 1
	s_barrier
	s_waitcnt lgkmcnt(0)
	v_mfma_f32_16x16x32_bf16 v[62:65], v[152:155], v[74:77], v[62:65]
	v_mfma_f32_16x16x32_bf16 v[58:61], v[160:163], v[74:77], v[58:61]
	v_mfma_f32_16x16x32_bf16 v[54:57], v[152:155], v[90:93], v[54:57]
	v_mfma_f32_16x16x32_bf16 v[50:53], v[160:163], v[90:93], v[50:53]
	v_mfma_f32_16x16x32_bf16 v[38:41], v[152:155], v[188:191], v[38:41]
	v_mfma_f32_16x16x32_bf16 v[34:37], v[160:163], v[188:191], v[34:37]
	v_mfma_f32_16x16x32_bf16 v[62:65], v[156:159], v[78:81], v[62:65]
	v_mfma_f32_16x16x32_bf16 v[58:61], v[164:167], v[78:81], v[58:61]
	v_mfma_f32_16x16x32_bf16 v[54:57], v[156:159], v[94:97], v[54:57]
	v_mfma_f32_16x16x32_bf16 v[50:53], v[164:167], v[94:97], v[50:53]
	v_mfma_f32_16x16x32_bf16 v[46:49], v[152:155], v[180:183], v[46:49]
	v_mfma_f32_16x16x32_bf16 v[42:45], v[160:163], v[180:183], v[42:45]
	v_mfma_f32_16x16x32_bf16 v[38:41], v[156:159], v[196:199], v[38:41]
	v_mfma_f32_16x16x32_bf16 v[34:37], v[164:167], v[196:199], v[34:37]
	v_mfma_f32_16x16x32_bf16 v[200:203], v[156:159], v[184:187], v[46:49]
	v_mfma_f32_16x16x32_bf16 v[216:219], v[164:167], v[184:187], v[42:45]
	s_setprio 0
	s_setprio 1
	v_mfma_f32_16x16x32_bf16 v[22:25], v[106:109], v[90:93], v[22:25]
	v_mfma_f32_16x16x32_bf16 v[18:21], v[204:207], v[90:93], v[18:21]
	v_mfma_f32_16x16x32_bf16 v[6:9], v[106:109], v[188:191], v[6:9]
	v_mfma_f32_16x16x32_bf16 v[2:5], v[204:207], v[188:191], v[2:5]
	v_mfma_f32_16x16x32_bf16 v[30:33], v[106:109], v[74:77], v[30:33]
	v_mfma_f32_16x16x32_bf16 v[26:29], v[204:207], v[74:77], v[26:29]
	v_mfma_f32_16x16x32_bf16 v[22:25], v[110:113], v[94:97], v[22:25]
	v_mfma_f32_16x16x32_bf16 v[18:21], v[208:211], v[94:97], v[18:21]
	v_mfma_f32_16x16x32_bf16 v[14:17], v[106:109], v[180:183], v[14:17]
	v_mfma_f32_16x16x32_bf16 v[10:13], v[204:207], v[180:183], v[10:13]
	v_mfma_f32_16x16x32_bf16 v[6:9], v[110:113], v[196:199], v[6:9]
	v_mfma_f32_16x16x32_bf16 v[2:5], v[208:211], v[196:199], v[2:5]
	v_mfma_f32_16x16x32_bf16 v[152:155], v[110:113], v[78:81], v[30:33]
	v_mfma_f32_16x16x32_bf16 v[156:159], v[208:211], v[78:81], v[26:29]
	v_mfma_f32_16x16x32_bf16 v[160:163], v[110:113], v[184:187], v[14:17]
	v_mfma_f32_16x16x32_bf16 v[164:167], v[208:211], v[184:187], v[10:13]
	s_barrier
	s_setprio 0
	s_nop 0
	ds_read_b128 v[10:13], v145
	ds_read_b128 v[14:17], v145 offset:1024
	ds_read_b128 v[180:183], v145 offset:2048
	ds_read_b128 v[144:147], v145 offset:3072
	ds_read_b128 v[26:29], v141 offset:32768
	ds_read_b128 v[30:33], v141 offset:33792
	ds_read_b128 v[42:45], v139 offset:32768
	ds_read_b128 v[46:49], v139 offset:33792
	ds_read_b128 v[184:187], v137 offset:32768
	ds_read_b128 v[188:191], v137 offset:33792
	ds_read_b128 v[196:199], v135 offset:32768
	ds_read_b128 v[204:207], v135 offset:33792
	s_waitcnt vmcnt(2)
	s_setprio 1
	s_barrier
	s_waitcnt lgkmcnt(0)
	v_mfma_f32_16x16x32_bf16 v[74:77], v[10:13], v[26:29], v[126:129]
	v_mfma_f32_16x16x32_bf16 v[126:129], v[14:17], v[30:33], v[74:77]
	v_mfma_f32_16x16x32_bf16 v[74:77], v[180:183], v[26:29], v[122:125]
	v_mfma_f32_16x16x32_bf16 v[122:125], v[144:147], v[30:33], v[74:77]
	v_mfma_f32_16x16x32_bf16 v[74:77], v[10:13], v[42:45], v[118:121]
	v_mfma_f32_16x16x32_bf16 v[110:113], v[14:17], v[46:49], v[74:77]
	v_mfma_f32_16x16x32_bf16 v[74:77], v[180:183], v[42:45], v[114:117]
	v_mfma_f32_16x16x32_bf16 v[106:109], v[144:147], v[46:49], v[74:77]
	v_mfma_f32_16x16x32_bf16 v[74:77], v[10:13], v[184:187], v[130:133]
	v_mfma_f32_16x16x32_bf16 v[94:97], v[14:17], v[188:191], v[74:77]
	v_mfma_f32_16x16x32_bf16 v[74:77], v[180:183], v[184:187], v[148:151]
	v_mfma_f32_16x16x32_bf16 v[90:93], v[144:147], v[188:191], v[74:77]
	v_mfma_f32_16x16x32_bf16 v[74:77], v[10:13], v[196:199], v[102:105]
	v_mfma_f32_16x16x32_bf16 v[78:81], v[14:17], v[204:207], v[74:77]
	v_mfma_f32_16x16x32_bf16 v[74:77], v[180:183], v[196:199], v[98:101]
	v_mfma_f32_16x16x32_bf16 v[74:77], v[144:147], v[204:207], v[74:77]
	s_barrier
;   #define LDA(dst,b,h) for(int m=0;m<4;++m)for(int k=0;k<2;++k) \
;     dst[m][k]=*reinterpret_cast<const bf16x8*>((char*)SA(b,h)+lds_byte(wr*64+m*16+fr,k*32+fq*8))
;   #define LDB(dst,b,h) for(int n=0;n<2;++n)for(int k=0;k<2;++k) \
;     dst[n][k]=*reinterpret_cast<const bf16x8*>((char*)SB(b,h)+lds_byte(wc*32+n*16+fr,k*32+fq*8))
;   #define MMA(ai,bj,At,Bt_) do{__builtin_amdgcn_s_setprio(1); \
;     for(int m=0;m<4;++m)for(int n=0;n<2;++n)for(int k=0;k<2;++k) \
;       acc[ai][bj][m][n]=__builtin_amdgcn_mfma_f32_16x16x32_bf16(Bt_[n][k],At[m][k],acc[ai][bj][m][n],0,0,0); \
;     __builtin_amdgcn_s_setprio(0);}while(0)
;   #define WAIT_V(n) asm volatile("s_waitcnt vmcnt(" #n ")":::"memory")
;   #define WAIT_L(n) asm volatile("s_waitcnt lgkmcnt(" #n ")":::"memory")
;   #define BAR __builtin_amdgcn_s_barrier()
; template <bool TWO, class MID> ...
;     ...
;   { LDB(B0,1,0); LDA(At,1,0); WAIT_V(2); BAR; WAIT_L(0); MMA(0,0,At,B0); BAR;
;     LDB(B1,1,1); WAIT_V(0); BAR; WAIT_L(0); MMA(0,1,At,B1); BAR;
;     LDA(At,1,1); BAR; WAIT_L(0); MMA(1,0,At,B0); MMA(1,1,At,B1); BAR; }
;   if(wr==0)BAR;
	s_setprio 0
	ds_read_b128 v[130:133], v143
	ds_read_b128 v[148:151], v143 offset:1024
	ds_read_b128 v[208:211], v143 offset:2048
	ds_read_b128 v[220:223], v143 offset:3072
	s_waitcnt vmcnt(0)
	s_setprio 1
	s_barrier
	s_waitcnt lgkmcnt(0)
	v_mfma_f32_16x16x32_bf16 v[98:101], v[130:133], v[26:29], v[212:215]
	v_mfma_f32_16x16x32_bf16 v[26:29], v[208:211], v[26:29], v[168:171]
	v_mfma_f32_16x16x32_bf16 v[114:117], v[220:223], v[30:33], v[26:29]
	v_mfma_f32_16x16x32_bf16 v[26:29], v[130:133], v[42:45], v[86:89]
	v_mfma_f32_16x16x32_bf16 v[102:105], v[148:151], v[46:49], v[26:29]
	v_mfma_f32_16x16x32_bf16 v[26:29], v[208:211], v[42:45], v[82:85]
	v_mfma_f32_16x16x32_bf16 v[118:121], v[148:151], v[30:33], v[98:101]
	v_mfma_f32_16x16x32_bf16 v[98:101], v[220:223], v[46:49], v[26:29]
	v_mfma_f32_16x16x32_bf16 v[26:29], v[130:133], v[184:187], v[172:175]
	v_mfma_f32_16x16x32_bf16 v[86:89], v[148:151], v[188:191], v[26:29]
	v_mfma_f32_16x16x32_bf16 v[26:29], v[208:211], v[184:187], v[176:179]
	v_mfma_f32_16x16x32_bf16 v[82:85], v[220:223], v[188:191], v[26:29]
	v_mfma_f32_16x16x32_bf16 v[26:29], v[130:133], v[196:199], v[70:73]
	v_mfma_f32_16x16x32_bf16 v[70:73], v[148:151], v[204:207], v[26:29]
	v_mfma_f32_16x16x32_bf16 v[26:29], v[208:211], v[196:199], v[66:69]
	v_mfma_f32_16x16x32_bf16 v[66:69], v[220:223], v[204:207], v[26:29]
	s_barrier
	s_setprio 0
	ds_read_b128 v[168:171], v141 offset:49152
	ds_read_b128 v[140:143], v141 offset:50176
	ds_read_b128 v[172:175], v139 offset:49152
	ds_read_b128 v[176:179], v139 offset:50176
	ds_read_b128 v[184:187], v137 offset:49152
	ds_read_b128 v[136:139], v137 offset:50176
	ds_read_b128 v[188:191], v135 offset:49152
	ds_read_b128 v[196:199], v135 offset:50176
	s_setprio 1
	s_barrier
	s_waitcnt lgkmcnt(0)
	v_mfma_f32_16x16x32_bf16 v[26:29], v[10:13], v[168:171], v[62:65]
	v_mfma_f32_16x16x32_bf16 v[62:65], v[14:17], v[140:143], v[26:29]
	v_mfma_f32_16x16x32_bf16 v[26:29], v[180:183], v[168:171], v[58:61]
	v_mfma_f32_16x16x32_bf16 v[58:61], v[144:147], v[140:143], v[26:29]
	v_mfma_f32_16x16x32_bf16 v[26:29], v[10:13], v[172:175], v[54:57]
	v_mfma_f32_16x16x32_bf16 v[46:49], v[14:17], v[176:179], v[26:29]
	v_mfma_f32_16x16x32_bf16 v[26:29], v[180:183], v[172:175], v[50:53]
	v_mfma_f32_16x16x32_bf16 v[42:45], v[144:147], v[176:179], v[26:29]
	v_mfma_f32_16x16x32_bf16 v[26:29], v[10:13], v[184:187], v[200:203]
	v_mfma_f32_16x16x32_bf16 v[10:13], v[10:13], v[188:191], v[38:41]
	v_mfma_f32_16x16x32_bf16 v[30:33], v[14:17], v[136:139], v[26:29]
	v_mfma_f32_16x16x32_bf16 v[26:29], v[180:183], v[184:187], v[216:219]
	v_mfma_f32_16x16x32_bf16 v[14:17], v[14:17], v[196:199], v[10:13]
	v_mfma_f32_16x16x32_bf16 v[10:13], v[180:183], v[188:191], v[34:37]
	v_mfma_f32_16x16x32_bf16 v[26:29], v[144:147], v[136:139], v[26:29]
	v_mfma_f32_16x16x32_bf16 v[10:13], v[144:147], v[196:199], v[10:13]
	s_setprio 0
	s_setprio 1
	v_mfma_f32_16x16x32_bf16 v[34:37], v[130:133], v[168:171], v[152:155]
	v_mfma_f32_16x16x32_bf16 v[54:57], v[148:151], v[140:143], v[34:37]
	v_mfma_f32_16x16x32_bf16 v[34:37], v[208:211], v[168:171], v[156:159]
	v_mfma_f32_16x16x32_bf16 v[18:21], v[208:211], v[172:175], v[18:21]
	v_mfma_f32_16x16x32_bf16 v[50:53], v[220:223], v[140:143], v[34:37]
	v_mfma_f32_16x16x32_bf16 v[22:25], v[130:133], v[172:175], v[22:25]
	v_mfma_f32_16x16x32_bf16 v[34:37], v[220:223], v[176:179], v[18:21]
	v_mfma_f32_16x16x32_bf16 v[18:21], v[130:133], v[184:187], v[160:163]
	v_mfma_f32_16x16x32_bf16 v[38:41], v[148:151], v[176:179], v[22:25]
	v_mfma_f32_16x16x32_bf16 v[22:25], v[148:151], v[136:139], v[18:21]
	v_mfma_f32_16x16x32_bf16 v[18:21], v[208:211], v[184:187], v[164:167]
	v_mfma_f32_16x16x32_bf16 v[6:9], v[130:133], v[188:191], v[6:9]
	v_mfma_f32_16x16x32_bf16 v[2:5], v[208:211], v[188:191], v[2:5]
	v_mfma_f32_16x16x32_bf16 v[18:21], v[220:223], v[136:139], v[18:21]
	v_mfma_f32_16x16x32_bf16 v[6:9], v[148:151], v[196:199], v[6:9]
	v_mfma_f32_16x16x32_bf16 v[2:5], v[220:223], v[196:199], v[2:5]
	s_setprio 0
	v_cmp_gt_u32_e32 vcc, s30, v1
	s_barrier
	s_and_saveexec_b64 s[0:1], vcc
	s_cbranch_execz .LBB0_623
	s_barrier
